# logits: f32 MFMA 4x4x1 + wf fragment image in LDS, staggered columns; attention counted LDS waits
# baseline (speedup 1.0000x reference)
.LBB0_278:
	s_mul_hi_u32 s14, s58, 0xaaaaaaab
	s_lshr_b32 s14, s14, 1
	s_mul_i32 s14, s14, 0xc000
	s_andn2_b64 vcc, exec, s[18:19]
	v_add_u32_e32 v0, s53, v191
	s_cbranch_vccnz .LBB0_280
	v_subrev_u32_e32 v3, s14, v184
	v_subrev_u32_e32 v2, s14, v185
	v_add_u32_e32 v14, v0, v3
	v_add_u32_e32 v15, v0, v2
	ds_read_b128 v[2:5], v14 offset:32768
	ds_read_b128 v[6:9], v14 offset:36864
	ds_read_b128 v[10:13], v15 offset:32768
	ds_read_b128 v[196:199], v15 offset:36864
	ds_read_b128 v[200:203], v14 offset:40960
	ds_read_b128 v[216:219], v14 offset:45056
	ds_read_b128 v[220:223], v15 offset:40960
	ds_read_b128 v[224:227], v15 offset:45056
	s_waitcnt lgkmcnt(7)
	v_mfma_f32_32x32x16_bf16 v[64:79], v[2:5], v[152:155], v[64:79]
	s_waitcnt lgkmcnt(6)
	v_mfma_f32_32x32x16_bf16 v[48:63], v[6:9], v[152:155], v[48:63]
	s_waitcnt lgkmcnt(3)
	v_mfma_f32_32x32x16_bf16 v[32:47], v[200:203], v[152:155], v[32:47]
	s_waitcnt lgkmcnt(2)
	v_mfma_f32_32x32x16_bf16 v[16:31], v[216:219], v[152:155], v[16:31]
	v_mfma_f32_32x32x16_bf16 v[64:79], v[10:13], v[156:159], v[64:79]
	v_mfma_f32_32x32x16_bf16 v[48:63], v[196:199], v[156:159], v[48:63]
	s_waitcnt lgkmcnt(1)
	v_mfma_f32_32x32x16_bf16 v[32:47], v[220:223], v[156:159], v[32:47]
	s_waitcnt lgkmcnt(0)
	v_mfma_f32_32x32x16_bf16 v[16:31], v[224:227], v[156:159], v[16:31]
.LBB0_280:
	s_andn2_b64 vcc, exec, s[16:17]
	s_cbranch_vccnz .LBB0_283
	v_subrev_u32_e32 v3, s14, v186
	v_subrev_u32_e32 v2, s14, v187
	v_add_u32_e32 v14, v0, v3
	v_add_u32_e32 v0, v0, v2
	ds_read_b128 v[2:5], v14 offset:32768
	ds_read_b128 v[6:9], v14 offset:36864
	ds_read_b128 v[10:13], v0 offset:32768
	ds_read_b128 v[196:199], v0 offset:36864
	ds_read_b128 v[200:203], v14 offset:40960
	ds_read_b128 v[216:219], v14 offset:45056
	ds_read_b128 v[220:223], v0 offset:40960
	ds_read_b128 v[224:227], v0 offset:45056
	s_waitcnt lgkmcnt(7)
	v_mfma_f32_32x32x16_bf16 v[64:79], v[2:5], v[144:147], v[64:79]
	s_waitcnt lgkmcnt(6)
	v_mfma_f32_32x32x16_bf16 v[48:63], v[6:9], v[144:147], v[48:63]
	s_waitcnt lgkmcnt(3)
	v_mfma_f32_32x32x16_bf16 v[32:47], v[200:203], v[144:147], v[32:47]
	s_waitcnt lgkmcnt(2)
	v_mfma_f32_32x32x16_bf16 v[16:31], v[216:219], v[144:147], v[16:31]
	v_mfma_f32_32x32x16_bf16 v[64:79], v[10:13], v[148:151], v[64:79]
	v_mfma_f32_32x32x16_bf16 v[48:63], v[196:199], v[148:151], v[48:63]
	s_waitcnt lgkmcnt(1)
	v_mfma_f32_32x32x16_bf16 v[32:47], v[220:223], v[148:151], v[32:47]
	s_waitcnt lgkmcnt(0)
	v_mfma_f32_32x32x16_bf16 v[16:31], v[224:227], v[148:151], v[16:31]
	s_branch .LBB0_283

.LBB0_283:
	s_add_i32 s36, s26, -2
	s_cmp_lt_u32 s36, s48
	s_cselect_b64 s[14:15], -1, 0
	s_cmp_ge_u32 s36, s48
	s_cbranch_scc1 .LBB0_288
	s_mul_hi_u32 s8, s59, 0xaaaaaaab
	s_lshr_b32 s8, s8, 1
	s_mul_i32 s8, s8, 0xc000
	s_sub_i32 s10, s28, 63
	v_subrev_u32_e32 v8, s8, v183
	v_subrev_u32_e32 v7, s8, v182
	v_subrev_u32_e32 v6, s8, v181
	v_subrev_u32_e32 v5, s8, v180
	v_subrev_u32_e32 v4, s8, v179
	v_subrev_u32_e32 v3, s8, v178
	v_subrev_u32_e32 v2, s8, v175
	v_subrev_u32_e32 v0, s8, v163
	s_cmp_le_i32 s10, s49
	v_add_u32_e32 v9, s53, v190
	s_cselect_b64 s[8:9], -1, 0
	s_cmp_gt_i32 s10, s49
	v_add_u32_e32 v0, v9, v0
	v_add_u32_e32 v2, v9, v2
	v_add_u32_e32 v3, v9, v3
	v_add_u32_e32 v4, v9, v4
	v_add_u32_e32 v5, v9, v5
	v_add_u32_e32 v6, v9, v6
	v_add_u32_e32 v7, v9, v7
	v_add_u32_e32 v8, v9, v8
	s_cbranch_scc1 .LBB0_286
	ds_read_b128 v[10:13], v0
	ds_read_b128 v[196:199], v2
	ds_read_b128 v[200:203], v3
	ds_read_b128 v[216:219], v4
	ds_read_b128 v[220:223], v5
	ds_read_b128 v[224:227], v6
	ds_read_b128 v[228:231], v7
	ds_read_b128 v[232:235], v8
	s_waitcnt lgkmcnt(7)
	v_mfma_f32_32x32x16_bf16 v[96:111], v[10:13], v[112:115], 0
	s_waitcnt lgkmcnt(6)
	v_mfma_f32_32x32x16_bf16 v[96:111], v[196:199], v[116:119], v[96:111]
	s_waitcnt lgkmcnt(5)
	v_mfma_f32_32x32x16_bf16 v[96:111], v[200:203], v[120:123], v[96:111]
	s_waitcnt lgkmcnt(4)
	v_mfma_f32_32x32x16_bf16 v[96:111], v[216:219], v[124:127], v[96:111]
	s_waitcnt lgkmcnt(3)
	v_mfma_f32_32x32x16_bf16 v[96:111], v[220:223], v[128:131], v[96:111]
	s_waitcnt lgkmcnt(2)
	v_mfma_f32_32x32x16_bf16 v[96:111], v[224:227], v[132:135], v[96:111]
	s_waitcnt lgkmcnt(1)
	v_mfma_f32_32x32x16_bf16 v[96:111], v[228:231], v[136:139], v[96:111]
	s_waitcnt lgkmcnt(0)
	v_mfma_f32_32x32x16_bf16 v[96:111], v[232:235], v[140:143], v[96:111]
.LBB0_286:
	s_cmp_ge_i32 s10, s29
	s_mov_b64 s[10:11], 0
	s_cbranch_scc1 .LBB0_288
	ds_read_b128 v[10:13], v0 offset:8192
	ds_read_b128 v[196:199], v2 offset:8192
	ds_read_b128 v[200:203], v3 offset:8192
	ds_read_b128 v[216:219], v4 offset:8192
	ds_read_b128 v[2:5], v5 offset:8192
	ds_read_b128 v[220:223], v6 offset:8192
	ds_read_b128 v[224:227], v7 offset:8192
	ds_read_b128 v[6:9], v8 offset:8192
	s_waitcnt lgkmcnt(7)
	v_mfma_f32_32x32x16_bf16 v[80:95], v[10:13], v[112:115], 0
	s_waitcnt lgkmcnt(6)
	v_mfma_f32_32x32x16_bf16 v[80:95], v[196:199], v[116:119], v[80:95]
	s_waitcnt lgkmcnt(5)
	v_mfma_f32_32x32x16_bf16 v[80:95], v[200:203], v[120:123], v[80:95]
	s_waitcnt lgkmcnt(4)
	v_mfma_f32_32x32x16_bf16 v[80:95], v[216:219], v[124:127], v[80:95]
	s_waitcnt lgkmcnt(3)
	v_mfma_f32_32x32x16_bf16 v[80:95], v[2:5], v[128:131], v[80:95]
	s_waitcnt lgkmcnt(2)
	v_mfma_f32_32x32x16_bf16 v[80:95], v[220:223], v[132:135], v[80:95]
	s_waitcnt lgkmcnt(1)
	v_mfma_f32_32x32x16_bf16 v[80:95], v[224:227], v[136:139], v[80:95]
	s_waitcnt lgkmcnt(0)
	v_mfma_f32_32x32x16_bf16 v[80:95], v[6:9], v[140:143], v[80:95]
	s_mov_b64 s[10:11], -1

.LBB0_350:
	s_mul_hi_u32 s14, s49, 0xaaaaaaab
	s_lshr_b32 s14, s14, 1
	s_mul_i32 s14, s14, 0xc000
	s_andn2_b64 vcc, exec, s[18:19]
	v_add_u32_e32 v0, s48, v192
	s_cbranch_vccnz .LBB0_352
	v_subrev_u32_e32 v3, s14, v185
	v_subrev_u32_e32 v2, s14, v186
	v_add_u32_e32 v14, v0, v3
	v_add_u32_e32 v15, v0, v2
	ds_read_b128 v[2:5], v14 offset:32768
	ds_read_b128 v[6:9], v14 offset:36864
	ds_read_b128 v[10:13], v15 offset:32768
	ds_read_b128 v[196:199], v15 offset:36864
	ds_read_b128 v[200:203], v14 offset:40960
	ds_read_b128 v[216:219], v14 offset:45056
	ds_read_b128 v[220:223], v15 offset:40960
	ds_read_b128 v[224:227], v15 offset:45056
	s_waitcnt lgkmcnt(7)
	v_mfma_f32_32x32x16_bf16 v[64:79], v[2:5], v[152:155], v[64:79]
	s_waitcnt lgkmcnt(6)
	v_mfma_f32_32x32x16_bf16 v[48:63], v[6:9], v[152:155], v[48:63]
	s_waitcnt lgkmcnt(3)
	v_mfma_f32_32x32x16_bf16 v[32:47], v[200:203], v[152:155], v[32:47]
	s_waitcnt lgkmcnt(2)
	v_mfma_f32_32x32x16_bf16 v[16:31], v[216:219], v[152:155], v[16:31]
	v_mfma_f32_32x32x16_bf16 v[64:79], v[10:13], v[156:159], v[64:79]
	v_mfma_f32_32x32x16_bf16 v[48:63], v[196:199], v[156:159], v[48:63]
	s_waitcnt lgkmcnt(1)
	v_mfma_f32_32x32x16_bf16 v[32:47], v[220:223], v[156:159], v[32:47]
	s_waitcnt lgkmcnt(0)
	v_mfma_f32_32x32x16_bf16 v[16:31], v[224:227], v[156:159], v[16:31]
.LBB0_352:
	s_andn2_b64 vcc, exec, s[16:17]
	s_cbranch_vccnz .LBB0_355
	v_subrev_u32_e32 v3, s14, v187
	v_subrev_u32_e32 v2, s14, v188
	v_add_u32_e32 v14, v0, v3
	v_add_u32_e32 v0, v0, v2
	ds_read_b128 v[2:5], v14 offset:32768
	ds_read_b128 v[6:9], v14 offset:36864
	ds_read_b128 v[10:13], v0 offset:32768
	ds_read_b128 v[196:199], v0 offset:36864
	ds_read_b128 v[200:203], v14 offset:40960
	ds_read_b128 v[216:219], v14 offset:45056
	ds_read_b128 v[220:223], v0 offset:40960
	ds_read_b128 v[224:227], v0 offset:45056
	s_waitcnt lgkmcnt(7)
	v_mfma_f32_32x32x16_bf16 v[64:79], v[2:5], v[144:147], v[64:79]
	s_waitcnt lgkmcnt(6)
	v_mfma_f32_32x32x16_bf16 v[48:63], v[6:9], v[144:147], v[48:63]
	s_waitcnt lgkmcnt(3)
	v_mfma_f32_32x32x16_bf16 v[32:47], v[200:203], v[144:147], v[32:47]
	s_waitcnt lgkmcnt(2)
	v_mfma_f32_32x32x16_bf16 v[16:31], v[216:219], v[144:147], v[16:31]
	v_mfma_f32_32x32x16_bf16 v[64:79], v[10:13], v[148:151], v[64:79]
	v_mfma_f32_32x32x16_bf16 v[48:63], v[196:199], v[148:151], v[48:63]
	s_waitcnt lgkmcnt(1)
	v_mfma_f32_32x32x16_bf16 v[32:47], v[220:223], v[148:151], v[32:47]
	s_waitcnt lgkmcnt(0)
	v_mfma_f32_32x32x16_bf16 v[16:31], v[224:227], v[148:151], v[16:31]
	s_branch .LBB0_355

.LBB0_355:
	s_cmp_lt_u32 s67, s58
	s_cselect_b64 s[14:15], -1, 0
	s_cmp_ge_u32 s67, s58
	s_cbranch_scc1 .LBB0_360
	s_mul_hi_u32 s8, s67, 0xaaaaaaab
	s_lshr_b32 s8, s8, 1
	s_mul_i32 s8, s8, 0xc000
	s_sub_i32 s10, s27, 63
	v_subrev_u32_e32 v8, s8, v184
	v_subrev_u32_e32 v7, s8, v183
	v_subrev_u32_e32 v6, s8, v182
	v_subrev_u32_e32 v5, s8, v181
	v_subrev_u32_e32 v4, s8, v180
	v_subrev_u32_e32 v3, s8, v179
	v_subrev_u32_e32 v2, s8, v178
	v_subrev_u32_e32 v0, s8, v163
	s_cmp_le_i32 s10, s63
	v_add_u32_e32 v9, s48, v191
	s_cselect_b64 s[8:9], -1, 0
	s_cmp_gt_i32 s10, s63
	v_add_u32_e32 v0, v9, v0
	v_add_u32_e32 v2, v9, v2
	v_add_u32_e32 v3, v9, v3
	v_add_u32_e32 v4, v9, v4
	v_add_u32_e32 v5, v9, v5
	v_add_u32_e32 v6, v9, v6
	v_add_u32_e32 v7, v9, v7
	v_add_u32_e32 v8, v9, v8
	s_cbranch_scc1 .LBB0_358
	ds_read_b128 v[10:13], v0
	ds_read_b128 v[196:199], v2
	ds_read_b128 v[200:203], v3
	ds_read_b128 v[216:219], v4
	ds_read_b128 v[220:223], v5
	ds_read_b128 v[224:227], v6
	ds_read_b128 v[228:231], v7
	ds_read_b128 v[232:235], v8
	s_waitcnt lgkmcnt(7)
	v_mfma_f32_32x32x16_bf16 v[96:111], v[10:13], v[112:115], 0
	s_waitcnt lgkmcnt(6)
	v_mfma_f32_32x32x16_bf16 v[96:111], v[196:199], v[116:119], v[96:111]
	s_waitcnt lgkmcnt(5)
	v_mfma_f32_32x32x16_bf16 v[96:111], v[200:203], v[120:123], v[96:111]
	s_waitcnt lgkmcnt(4)
	v_mfma_f32_32x32x16_bf16 v[96:111], v[216:219], v[124:127], v[96:111]
	s_waitcnt lgkmcnt(3)
	v_mfma_f32_32x32x16_bf16 v[96:111], v[220:223], v[128:131], v[96:111]
	s_waitcnt lgkmcnt(2)
	v_mfma_f32_32x32x16_bf16 v[96:111], v[224:227], v[132:135], v[96:111]
	s_waitcnt lgkmcnt(1)
	v_mfma_f32_32x32x16_bf16 v[96:111], v[228:231], v[136:139], v[96:111]
	s_waitcnt lgkmcnt(0)
	v_mfma_f32_32x32x16_bf16 v[96:111], v[232:235], v[140:143], v[96:111]
.LBB0_358:
	s_cmp_ge_i32 s10, s52
	s_mov_b64 s[10:11], 0
	s_cbranch_scc1 .LBB0_360
	ds_read_b128 v[10:13], v0 offset:8192
	ds_read_b128 v[196:199], v2 offset:8192
	ds_read_b128 v[200:203], v3 offset:8192
	ds_read_b128 v[216:219], v4 offset:8192
	ds_read_b128 v[2:5], v5 offset:8192
	ds_read_b128 v[220:223], v6 offset:8192
	ds_read_b128 v[224:227], v7 offset:8192
	ds_read_b128 v[6:9], v8 offset:8192
	s_waitcnt lgkmcnt(7)
	v_mfma_f32_32x32x16_bf16 v[80:95], v[10:13], v[112:115], 0
	s_waitcnt lgkmcnt(6)
	v_mfma_f32_32x32x16_bf16 v[80:95], v[196:199], v[116:119], v[80:95]
	s_waitcnt lgkmcnt(5)
	v_mfma_f32_32x32x16_bf16 v[80:95], v[200:203], v[120:123], v[80:95]
	s_waitcnt lgkmcnt(4)
	v_mfma_f32_32x32x16_bf16 v[80:95], v[216:219], v[124:127], v[80:95]
	s_waitcnt lgkmcnt(3)
	v_mfma_f32_32x32x16_bf16 v[80:95], v[2:5], v[128:131], v[80:95]
	s_waitcnt lgkmcnt(2)
	v_mfma_f32_32x32x16_bf16 v[80:95], v[220:223], v[132:135], v[80:95]
	s_waitcnt lgkmcnt(1)
	v_mfma_f32_32x32x16_bf16 v[80:95], v[224:227], v[136:139], v[80:95]
	s_waitcnt lgkmcnt(0)
	v_mfma_f32_32x32x16_bf16 v[80:95], v[6:9], v[140:143], v[80:95]
	s_mov_b64 s[10:11], -1

.LBB0_425:
	s_mul_hi_u32 s14, s63, 0xaaaaaaab
	s_lshr_b32 s14, s14, 1
	s_mul_i32 s14, s14, 0xc000
	s_andn2_b64 vcc, exec, s[18:19]
	v_add_u32_e32 v0, s1, v192
	s_cbranch_vccnz .LBB0_427
	v_subrev_u32_e32 v3, s14, v185
	v_subrev_u32_e32 v2, s14, v186
	v_add_u32_e32 v14, v0, v3
	v_add_u32_e32 v15, v0, v2
	ds_read_b128 v[2:5], v14 offset:32768
	ds_read_b128 v[6:9], v14 offset:36864
	ds_read_b128 v[10:13], v15 offset:32768
	ds_read_b128 v[196:199], v15 offset:36864
	ds_read_b128 v[200:203], v14 offset:40960
	ds_read_b128 v[216:219], v14 offset:45056
	ds_read_b128 v[220:223], v15 offset:40960
	ds_read_b128 v[224:227], v15 offset:45056
	s_waitcnt lgkmcnt(7)
	v_mfma_f32_32x32x16_bf16 v[64:79], v[2:5], v[152:155], v[64:79]
	s_waitcnt lgkmcnt(6)
	v_mfma_f32_32x32x16_bf16 v[48:63], v[6:9], v[152:155], v[48:63]
	s_waitcnt lgkmcnt(3)
	v_mfma_f32_32x32x16_bf16 v[32:47], v[200:203], v[152:155], v[32:47]
	s_waitcnt lgkmcnt(2)
	v_mfma_f32_32x32x16_bf16 v[16:31], v[216:219], v[152:155], v[16:31]
	v_mfma_f32_32x32x16_bf16 v[64:79], v[10:13], v[156:159], v[64:79]
	v_mfma_f32_32x32x16_bf16 v[48:63], v[196:199], v[156:159], v[48:63]
	s_waitcnt lgkmcnt(1)
	v_mfma_f32_32x32x16_bf16 v[32:47], v[220:223], v[156:159], v[32:47]
	s_waitcnt lgkmcnt(0)
	v_mfma_f32_32x32x16_bf16 v[16:31], v[224:227], v[156:159], v[16:31]

.LBB0_430:
	s_add_i32 s36, s51, -2
	s_cmp_lt_u32 s36, s53
	s_cselect_b64 s[14:15], -1, 0
	s_cmp_ge_u32 s36, s53
	s_cbranch_scc1 .LBB0_435
	s_mul_hi_u32 s8, s66, 0xaaaaaaab
	s_lshr_b32 s8, s8, 1
	s_mul_i32 s8, s8, 0xc000
	s_sub_i32 s10, s28, 63
	v_subrev_u32_e32 v8, s8, v184
	v_subrev_u32_e32 v7, s8, v183
	v_subrev_u32_e32 v6, s8, v182
	v_subrev_u32_e32 v5, s8, v181
	v_subrev_u32_e32 v4, s8, v180
	v_subrev_u32_e32 v3, s8, v179
	v_subrev_u32_e32 v2, s8, v178
	v_subrev_u32_e32 v0, s8, v163
	s_cmp_le_i32 s10, s58
	v_add_u32_e32 v9, s1, v191
	s_cselect_b64 s[8:9], -1, 0
	s_cmp_gt_i32 s10, s58
	v_add_u32_e32 v0, v9, v0
	v_add_u32_e32 v2, v9, v2
	v_add_u32_e32 v3, v9, v3
	v_add_u32_e32 v4, v9, v4
	v_add_u32_e32 v5, v9, v5
	v_add_u32_e32 v6, v9, v6
	v_add_u32_e32 v7, v9, v7
	v_add_u32_e32 v8, v9, v8
	s_cbranch_scc1 .LBB0_433
	ds_read_b128 v[10:13], v0
	ds_read_b128 v[196:199], v2
	ds_read_b128 v[200:203], v3
	ds_read_b128 v[216:219], v4
	ds_read_b128 v[220:223], v5
	ds_read_b128 v[224:227], v6
	ds_read_b128 v[228:231], v7
	ds_read_b128 v[232:235], v8
	s_waitcnt lgkmcnt(7)
	v_mfma_f32_32x32x16_bf16 v[96:111], v[10:13], v[112:115], 0
	s_waitcnt lgkmcnt(6)
	v_mfma_f32_32x32x16_bf16 v[96:111], v[196:199], v[116:119], v[96:111]
	s_waitcnt lgkmcnt(5)
	v_mfma_f32_32x32x16_bf16 v[96:111], v[200:203], v[120:123], v[96:111]
	s_waitcnt lgkmcnt(4)
	v_mfma_f32_32x32x16_bf16 v[96:111], v[216:219], v[124:127], v[96:111]
	s_waitcnt lgkmcnt(3)
	v_mfma_f32_32x32x16_bf16 v[96:111], v[220:223], v[128:131], v[96:111]
	s_waitcnt lgkmcnt(2)
	v_mfma_f32_32x32x16_bf16 v[96:111], v[224:227], v[132:135], v[96:111]
	s_waitcnt lgkmcnt(1)
	v_mfma_f32_32x32x16_bf16 v[96:111], v[228:231], v[136:139], v[96:111]
	s_waitcnt lgkmcnt(0)
	v_mfma_f32_32x32x16_bf16 v[96:111], v[232:235], v[140:143], v[96:111]
.LBB0_433:
	s_cmp_ge_i32 s10, s49
	s_mov_b64 s[10:11], 0
	s_cbranch_scc1 .LBB0_435
	ds_read_b128 v[10:13], v0 offset:8192
	ds_read_b128 v[196:199], v2 offset:8192
	ds_read_b128 v[200:203], v3 offset:8192
	ds_read_b128 v[216:219], v4 offset:8192
	ds_read_b128 v[2:5], v5 offset:8192
	ds_read_b128 v[220:223], v6 offset:8192
	ds_read_b128 v[224:227], v7 offset:8192
	ds_read_b128 v[6:9], v8 offset:8192
	s_waitcnt lgkmcnt(7)
	v_mfma_f32_32x32x16_bf16 v[80:95], v[10:13], v[112:115], 0
	s_waitcnt lgkmcnt(6)
	v_mfma_f32_32x32x16_bf16 v[80:95], v[196:199], v[116:119], v[80:95]
	s_waitcnt lgkmcnt(5)
	v_mfma_f32_32x32x16_bf16 v[80:95], v[200:203], v[120:123], v[80:95]
	s_waitcnt lgkmcnt(4)
	v_mfma_f32_32x32x16_bf16 v[80:95], v[216:219], v[124:127], v[80:95]
	s_waitcnt lgkmcnt(3)
	v_mfma_f32_32x32x16_bf16 v[80:95], v[2:5], v[128:131], v[80:95]
	s_waitcnt lgkmcnt(2)
	v_mfma_f32_32x32x16_bf16 v[80:95], v[220:223], v[132:135], v[80:95]
	s_waitcnt lgkmcnt(1)
	v_mfma_f32_32x32x16_bf16 v[80:95], v[224:227], v[136:139], v[80:95]
	s_waitcnt lgkmcnt(0)
	v_mfma_f32_32x32x16_bf16 v[80:95], v[6:9], v[140:143], v[80:95]
	s_mov_b64 s[10:11], -1

.LBB0_498:
	s_mul_hi_u32 s14, s49, 0xaaaaaaab
	s_lshr_b32 s14, s14, 1
	s_mul_i32 s14, s14, 0xc000
	s_andn2_b64 vcc, exec, s[18:19]
	v_add_u32_e32 v152, s48, v185
	s_cbranch_vccnz .LBB0_500
	v_subrev_u32_e32 v154, s14, v178
	v_subrev_u32_e32 v153, s14, v179
	v_add_u32_e32 v158, v152, v154
	v_add_u32_e32 v153, v152, v153
	ds_read_b128 v[154:157], v158 offset:32768
	ds_read_b128 v[190:193], v158 offset:36864
	ds_read_b128 v[194:197], v153 offset:32768
	ds_read_b128 v[198:201], v153 offset:36864
	ds_read_b128 v[216:219], v158 offset:40960
	ds_read_b128 v[220:223], v158 offset:45056
	ds_read_b128 v[224:227], v153 offset:40960
	ds_read_b128 v[228:231], v153 offset:45056
	s_waitcnt lgkmcnt(7)
	v_mfma_f32_32x32x16_bf16 v[34:49], v[154:157], v[138:141], v[34:49]
	s_waitcnt lgkmcnt(6)
	v_mfma_f32_32x32x16_bf16 v[50:65], v[190:193], v[138:141], v[50:65]
	s_waitcnt lgkmcnt(3)
	v_mfma_f32_32x32x16_bf16 v[18:33], v[216:219], v[138:141], v[18:33]
	s_waitcnt lgkmcnt(2)
	v_mfma_f32_32x32x16_bf16 v[2:17], v[220:223], v[138:141], v[2:17]
	v_mfma_f32_32x32x16_bf16 v[34:49], v[194:197], v[142:145], v[34:49]
	v_mfma_f32_32x32x16_bf16 v[50:65], v[198:201], v[142:145], v[50:65]
	s_waitcnt lgkmcnt(1)
	v_mfma_f32_32x32x16_bf16 v[18:33], v[224:227], v[142:145], v[18:33]
	s_waitcnt lgkmcnt(0)
	v_mfma_f32_32x32x16_bf16 v[2:17], v[228:231], v[142:145], v[2:17]
.LBB0_500:
	s_andn2_b64 vcc, exec, s[16:17]
	s_cbranch_vccnz .LBB0_503
	v_subrev_u32_e32 v154, s14, v180
	v_subrev_u32_e32 v153, s14, v181
	v_add_u32_e32 v189, v152, v154
	v_add_u32_e32 v202, v152, v153
	ds_read_b128 v[152:155], v189 offset:32768
	ds_read_b128 v[156:159], v189 offset:36864
	ds_read_b128 v[190:193], v202 offset:32768
	ds_read_b128 v[194:197], v202 offset:36864
	ds_read_b128 v[198:201], v189 offset:40960
	ds_read_b128 v[216:219], v189 offset:45056
	ds_read_b128 v[220:223], v202 offset:40960
	ds_read_b128 v[224:227], v202 offset:45056
	s_waitcnt lgkmcnt(7)
	v_mfma_f32_32x32x16_bf16 v[34:49], v[152:155], v[130:133], v[34:49]
	s_waitcnt lgkmcnt(6)
	v_mfma_f32_32x32x16_bf16 v[50:65], v[156:159], v[130:133], v[50:65]
	s_waitcnt lgkmcnt(3)
	v_mfma_f32_32x32x16_bf16 v[18:33], v[198:201], v[130:133], v[18:33]
	s_waitcnt lgkmcnt(2)
	v_mfma_f32_32x32x16_bf16 v[2:17], v[216:219], v[130:133], v[2:17]
	v_mfma_f32_32x32x16_bf16 v[34:49], v[190:193], v[134:137], v[34:49]
	v_mfma_f32_32x32x16_bf16 v[50:65], v[194:197], v[134:137], v[50:65]
	s_waitcnt lgkmcnt(1)
	v_mfma_f32_32x32x16_bf16 v[18:33], v[220:223], v[134:137], v[18:33]
	s_waitcnt lgkmcnt(0)
	v_mfma_f32_32x32x16_bf16 v[2:17], v[224:227], v[134:137], v[2:17]
	s_branch .LBB0_503

.LBB0_503:
	s_add_i32 s36, s46, -2
	s_cmp_lt_u32 s36, s23
	s_cselect_b64 s[14:15], -1, 0
	s_cmp_ge_u32 s36, s23
	s_cbranch_scc1 .LBB0_508
	s_mul_hi_u32 s8, s50, 0xaaaaaaab
	s_lshr_b32 s8, s8, 1
	s_mul_i32 s8, s8, 0xc000
	s_sub_i32 s10, s26, 63
	v_subrev_u32_e32 v159, s8, v177
	v_subrev_u32_e32 v158, s8, v176
	v_subrev_u32_e32 v157, s8, v165
	v_subrev_u32_e32 v156, s8, v164
	v_subrev_u32_e32 v155, s8, v163
	v_subrev_u32_e32 v154, s8, v162
	v_subrev_u32_e32 v153, s8, v161
	v_subrev_u32_e32 v152, s8, v160
	s_cmp_le_i32 s10, s24
	v_add_u32_e32 v189, s48, v184
	s_cselect_b64 s[8:9], -1, 0
	s_cmp_gt_i32 s10, s24
	v_add_u32_e32 v152, v189, v152
	v_add_u32_e32 v153, v189, v153
	v_add_u32_e32 v154, v189, v154
	v_add_u32_e32 v155, v189, v155
	v_add_u32_e32 v156, v189, v156
	v_add_u32_e32 v157, v189, v157
	v_add_u32_e32 v158, v189, v158
	v_add_u32_e32 v159, v189, v159
	s_cbranch_scc1 .LBB0_506
	ds_read_b128 v[82:85], v152
	ds_read_b128 v[190:193], v153
	ds_read_b128 v[194:197], v154
	ds_read_b128 v[198:201], v155
	ds_read_b128 v[216:219], v156
	ds_read_b128 v[220:223], v157
	ds_read_b128 v[224:227], v158
	ds_read_b128 v[228:231], v159
	s_waitcnt lgkmcnt(7)
	v_mfma_f32_32x32x16_bf16 v[82:97], v[82:85], v[98:101], 0
	s_waitcnt lgkmcnt(6)
	v_mfma_f32_32x32x16_bf16 v[82:97], v[190:193], v[102:105], v[82:97]
	s_waitcnt lgkmcnt(5)
	v_mfma_f32_32x32x16_bf16 v[82:97], v[194:197], v[106:109], v[82:97]
	s_waitcnt lgkmcnt(4)
	v_mfma_f32_32x32x16_bf16 v[82:97], v[198:201], v[110:113], v[82:97]
	s_waitcnt lgkmcnt(3)
	v_mfma_f32_32x32x16_bf16 v[82:97], v[216:219], v[114:117], v[82:97]
	s_waitcnt lgkmcnt(2)
	v_mfma_f32_32x32x16_bf16 v[82:97], v[220:223], v[118:121], v[82:97]
	s_waitcnt lgkmcnt(1)
	v_mfma_f32_32x32x16_bf16 v[82:97], v[224:227], v[122:125], v[82:97]
	s_waitcnt lgkmcnt(0)
	v_mfma_f32_32x32x16_bf16 v[82:97], v[228:231], v[126:129], v[82:97]
.LBB0_506:
	s_cmp_ge_i32 s10, s28
	s_mov_b64 s[10:11], 0
	s_cbranch_scc1 .LBB0_508
	ds_read_b128 v[66:69], v152 offset:8192
	ds_read_b128 v[190:193], v153 offset:8192
	ds_read_b128 v[194:197], v154 offset:8192
	ds_read_b128 v[152:155], v155 offset:8192
	ds_read_b128 v[198:201], v156 offset:8192
	ds_read_b128 v[216:219], v157 offset:8192
	ds_read_b128 v[220:223], v158 offset:8192
	ds_read_b128 v[156:159], v159 offset:8192
	s_waitcnt lgkmcnt(7)
	v_mfma_f32_32x32x16_bf16 v[66:81], v[66:69], v[98:101], 0
	s_waitcnt lgkmcnt(6)
	v_mfma_f32_32x32x16_bf16 v[66:81], v[190:193], v[102:105], v[66:81]
	s_waitcnt lgkmcnt(5)
	v_mfma_f32_32x32x16_bf16 v[66:81], v[194:197], v[106:109], v[66:81]
	s_waitcnt lgkmcnt(4)
	v_mfma_f32_32x32x16_bf16 v[66:81], v[152:155], v[110:113], v[66:81]
	s_waitcnt lgkmcnt(3)
	v_mfma_f32_32x32x16_bf16 v[66:81], v[198:201], v[114:117], v[66:81]
	s_waitcnt lgkmcnt(2)
	v_mfma_f32_32x32x16_bf16 v[66:81], v[216:219], v[118:121], v[66:81]
	s_waitcnt lgkmcnt(1)
	v_mfma_f32_32x32x16_bf16 v[66:81], v[220:223], v[122:125], v[66:81]
	s_waitcnt lgkmcnt(0)
	v_mfma_f32_32x32x16_bf16 v[66:81], v[156:159], v[126:129], v[66:81]
	s_mov_b64 s[10:11], -1

; __device__ __forceinline__ int opaque_tid() { int t = threadIdx.x; asm volatile("" : "+v"(t)); return t; }
; __global__ void __launch_bounds__(NWAVES * 64, 2) fwd_megakernel(Args args) {
;     ...
;         if (j == 2) {
;             const int ln = opaque_tid() & 63;
;             float wreg[32];
; #pragma unroll
;             for (int jj = 0; jj < 4; ++jj) { const f32x4 a = *(const f32x4*)(wf + (size_t)wave * DM + 512 * jj + 8 * ln), bq = *(const f32x4*)(wf + (size_t)wave * DM + 512 * jj + 8 * ln + 4);
; #pragma unroll
;                 for (int e = 0; e < 4; ++e) { wreg[8 * jj + e] = a[e]; wreg[8 * jj + 4 + e] = bq[e]; } }
;             const float bf = args.in[8][wave];
;             for (int m0 = vcu2 * 4; m0 < M; m0 += G * 4) {
;                 u32x4 pw[4][4]; float sq[4];
; #pragma unroll
;                 for (int q = 0; q < 4; ++q) { sq[q] = ss[M + m0 + q];
; #pragma unroll
;                     for (int jj = 0; jj < 4; ++jj) pw[q][jj] = *(const u32x4*)(XB + (size_t)(m0 + q) * DM + 512 * jj + 8 * ln); }
.LBB0_591:
	s_and_b64 vcc, exec, s[4:5]
	s_cbranch_vccz .LBB0_605
	s_cmp_gt_i32 s39, 1
	s_cbranch_scc0 .LBB0_606
	s_cmp_lt_i32 s39, 3
	s_mov_b64 s[4:5], -1
	s_cbranch_scc0 .LBB0_607
	v_lshrrev_b32_e32 v0, 6, v166
	v_readlane_b32 s4, v249, 1
	v_readfirstlane_b32 s12, v0
	s_lshl_b32 s4, s4, 4
	s_cmpk_gt_i32 s4, 0x3fff
	s_cbranch_scc1 .Llg_done
	v_lshlrev_b32_e32 v0, 4, v166
	s_add_u32 s8, s60, 0x100000
	s_addc_u32 s9, s61, 0
	global_load_dwordx4 v[36:39], v0, s[8:9]
	s_add_u32 s8, s8, 0x2000
	s_addc_u32 s9, s9, 0
	global_load_dwordx4 v[40:43], v0, s[8:9]
	s_add_u32 s8, s8, 0x2000
	s_addc_u32 s9, s9, 0
	global_load_dwordx4 v[44:47], v0, s[8:9]
	s_add_u32 s8, s8, 0x2000
	s_addc_u32 s9, s9, 0
	global_load_dwordx4 v[48:51], v0, s[8:9]
	s_add_u32 s8, s8, 0x2000
	s_addc_u32 s9, s9, 0
	global_load_dwordx4 v[52:55], v0, s[8:9]
	s_add_u32 s8, s8, 0x2000
	s_addc_u32 s9, s9, 0
	global_load_dwordx4 v[56:59], v0, s[8:9]
	s_add_u32 s8, s8, 0x2000
	s_addc_u32 s9, s9, 0
	global_load_dwordx4 v[60:63], v0, s[8:9]
	s_add_u32 s8, s8, 0x2000
	s_addc_u32 s9, s9, 0
	global_load_dwordx4 v[64:67], v0, s[8:9]
	v_lshrrev_b32_e32 v4, 5, v166
	v_lshlrev_b32_e32 v4, 12, v4
	v_and_b32_e32 v5, 1, v166
	v_lshl_or_b32 v4, v5, 10, v4
	v_bfe_u32 v5, v166, 1, 4
	v_lshl_or_b32 v4, v5, 6, v4
	v_and_b32_e32 v5, 3, v168
	v_lshrrev_b32_e32 v6, 2, v168
	v_lshlrev_b32_e32 v5, 12, v5
	v_lshl_or_b32 v2, v6, 4, v5
	v_lshlrev_b32_e32 v3, 4, v168
	v_add_u32_e32 v116, 0x4000, v2
	v_readlane_b32 s16, v250, 63
	v_readlane_b32 s17, v249, 0
	s_lshl_b32 s5, s12, 2
	s_sub_u32 s16, s16, s5
	s_subb_u32 s17, s17, 0
	s_mov_b32 s18, 0xbfb8aa3b
	s_mov_b32 s19, 0x3f317218
	s_waitcnt vmcnt(7)
	ds_write_b128 v4, v[36:39] offset:0
	s_waitcnt vmcnt(6)
	ds_write_b128 v4, v[40:43] offset:16
	s_waitcnt vmcnt(5)
	ds_write_b128 v4, v[44:47] offset:32
	s_waitcnt vmcnt(4)
	ds_write_b128 v4, v[48:51] offset:48
	s_waitcnt vmcnt(3)
	ds_write_b128 v4, v[52:55] offset:2048
	s_waitcnt vmcnt(2)
	ds_write_b128 v4, v[56:59] offset:2064
	s_waitcnt vmcnt(1)
	ds_write_b128 v4, v[60:63] offset:2080
	s_waitcnt vmcnt(0)
	ds_write_b128 v4, v[64:67] offset:2096
	s_waitcnt lgkmcnt(0)
	s_barrier
.Llg_trip:
	s_lshl_b32 s5, s12, 3
	s_add_u32 s5, s5, s4
	s_lshl_b32 s5, s5, 12
	s_add_u32 s6, s94, s5
	s_addc_u32 s7, s95, 0
	s_lshr_b32 s13, s4, 6
	s_lshl_b32 s1, s12, 1
	s_add_i32 s13, s13, s1
	v_mov_b32_e32 v4, 0
	v_mov_b32_e32 v5, 0
	v_mov_b32_e32 v6, 0
	v_mov_b32_e32 v7, 0
	v_mov_b32_e32 v8, 0
	v_mov_b32_e32 v9, 0
	v_mov_b32_e32 v10, 0
	v_mov_b32_e32 v11, 0
	v_mov_b32_e32 v12, 0
	v_mov_b32_e32 v13, 0
	v_mov_b32_e32 v14, 0
	v_mov_b32_e32 v15, 0
	v_mov_b32_e32 v16, 0
	v_mov_b32_e32 v17, 0
	v_mov_b32_e32 v18, 0
	v_mov_b32_e32 v19, 0
	s_add_i32 s1, s13, 0
	s_and_b32 s1, s1, 15
	s_lshl_b32 s1, s1, 8
	s_add_u32 s10, s6, s1
	s_addc_u32 s11, s7, 0
	global_load_dwordx4 v[36:39], v2, s[10:11]
	global_load_dwordx4 v[40:43], v116, s[10:11]
	s_add_i32 s1, s13, 1
	s_and_b32 s1, s1, 15
	s_lshl_b32 s1, s1, 8
	s_add_u32 s10, s6, s1
	s_addc_u32 s11, s7, 0
	global_load_dwordx4 v[44:47], v2, s[10:11]
	global_load_dwordx4 v[48:51], v116, s[10:11]
	s_add_i32 s1, s13, 2
	s_and_b32 s1, s1, 15
	s_lshl_b32 s1, s1, 8
	s_add_u32 s10, s6, s1
	s_addc_u32 s11, s7, 0
	global_load_dwordx4 v[52:55], v2, s[10:11]
	global_load_dwordx4 v[56:59], v116, s[10:11]
	s_add_i32 s1, s13, 3
	s_and_b32 s1, s1, 15
	s_lshl_b32 s1, s1, 8
	s_add_u32 s10, s6, s1
	s_addc_u32 s11, s7, 0
	global_load_dwordx4 v[60:63], v2, s[10:11]
	global_load_dwordx4 v[64:67], v116, s[10:11]
	s_add_i32 s1, s13, 4
	s_and_b32 s1, s1, 15
	s_lshl_b32 s1, s1, 8
	s_add_u32 s10, s6, s1
	s_addc_u32 s11, s7, 0
	global_load_dwordx4 v[68:71], v2, s[10:11]
	global_load_dwordx4 v[72:75], v116, s[10:11]
	s_add_i32 s1, s13, 0
	s_and_b32 s1, s1, 15
	s_lshl_b32 s1, s1, 12
	v_add_u32_e32 v117, s1, v3
	ds_read_b128 v[84:87], v117 offset:0
	ds_read_b128 v[88:91], v117 offset:1024
	ds_read_b128 v[92:95], v117 offset:2048
	ds_read_b128 v[96:99], v117 offset:3072
	s_waitcnt vmcnt(8)
	v_lshlrev_b32_e32 v20, 16, v36
	v_and_b32_e32 v36, 0xffff0000, v36
	v_lshlrev_b32_e32 v21, 16, v37
	v_and_b32_e32 v37, 0xffff0000, v37
	v_lshlrev_b32_e32 v22, 16, v38
	v_and_b32_e32 v38, 0xffff0000, v38
	v_lshlrev_b32_e32 v23, 16, v39
	v_and_b32_e32 v39, 0xffff0000, v39
	v_lshlrev_b32_e32 v24, 16, v40
	v_and_b32_e32 v40, 0xffff0000, v40
	v_lshlrev_b32_e32 v25, 16, v41
	v_and_b32_e32 v41, 0xffff0000, v41
	v_lshlrev_b32_e32 v26, 16, v42
	v_and_b32_e32 v42, 0xffff0000, v42
	v_lshlrev_b32_e32 v27, 16, v43
	v_and_b32_e32 v43, 0xffff0000, v43
	s_add_i32 s1, s13, 5
	s_and_b32 s1, s1, 15
	s_lshl_b32 s1, s1, 8
	s_add_u32 s10, s6, s1
	s_addc_u32 s11, s7, 0
	global_load_dwordx4 v[76:79], v2, s[10:11]
	global_load_dwordx4 v[80:83], v116, s[10:11]
	s_add_i32 s1, s13, 1
	s_and_b32 s1, s1, 15
	s_lshl_b32 s1, s1, 12
	v_add_u32_e32 v117, s1, v3
	ds_read_b128 v[100:103], v117 offset:0
	ds_read_b128 v[104:107], v117 offset:1024
	ds_read_b128 v[108:111], v117 offset:2048
	ds_read_b128 v[112:115], v117 offset:3072
	s_waitcnt vmcnt(8)
	s_waitcnt lgkmcnt(4)
; __global__ void __launch_bounds__(NWAVES * 64, 2) fwd_megakernel(Args args) {
;     ...
;                 for (int q = 0; q < 4; ++q) { float d = 0.f;
; #pragma unroll
;                     for (int jj = 0; jj < 4; ++jj) { const u32x4 w = pw[q][jj];
;                         d += __uint_as_float(w.x << 16) * wreg[8 * jj + 0] + __uint_as_float(w.x & 0xffff0000u) * wreg[8 * jj + 1] + __uint_as_float(w.y << 16) * wreg[8 * jj + 2] + __uint_as_float(w.y & 0xffff0000u) * wreg[8 * jj + 3]
;                            + __uint_as_float(w.z << 16) * wreg[8 * jj + 4] + __uint_as_float(w.z & 0xffff0000u) * wreg[8 * jj + 5] + __uint_as_float(w.w << 16) * wreg[8 * jj + 6] + __uint_as_float(w.w & 0xffff0000u) * wreg[8 * jj + 7]; }
	v_mfma_f32_4x4x1_16b_f32 v[4:7], v20, v84, v[4:7]
	v_mfma_f32_4x4x1_16b_f32 v[8:11], v20, v92, v[8:11]
	v_lshlrev_b32_e32 v28, 16, v44
	v_mfma_f32_4x4x1_16b_f32 v[12:15], v24, v84, v[12:15]
	v_mfma_f32_4x4x1_16b_f32 v[16:19], v24, v92, v[16:19]
	v_and_b32_e32 v44, 0xffff0000, v44
	v_mfma_f32_4x4x1_16b_f32 v[4:7], v36, v85, v[4:7]
	v_mfma_f32_4x4x1_16b_f32 v[8:11], v36, v93, v[8:11]
	v_lshlrev_b32_e32 v29, 16, v45
	v_mfma_f32_4x4x1_16b_f32 v[12:15], v40, v85, v[12:15]
	v_mfma_f32_4x4x1_16b_f32 v[16:19], v40, v93, v[16:19]
	v_and_b32_e32 v45, 0xffff0000, v45
	v_mfma_f32_4x4x1_16b_f32 v[4:7], v21, v86, v[4:7]
	v_mfma_f32_4x4x1_16b_f32 v[8:11], v21, v94, v[8:11]
	v_lshlrev_b32_e32 v30, 16, v46
	v_mfma_f32_4x4x1_16b_f32 v[12:15], v25, v86, v[12:15]
	v_mfma_f32_4x4x1_16b_f32 v[16:19], v25, v94, v[16:19]
	v_and_b32_e32 v46, 0xffff0000, v46
	v_mfma_f32_4x4x1_16b_f32 v[4:7], v37, v87, v[4:7]
	v_mfma_f32_4x4x1_16b_f32 v[8:11], v37, v95, v[8:11]
	v_lshlrev_b32_e32 v31, 16, v47
	v_mfma_f32_4x4x1_16b_f32 v[12:15], v41, v87, v[12:15]
	v_mfma_f32_4x4x1_16b_f32 v[16:19], v41, v95, v[16:19]
	v_and_b32_e32 v47, 0xffff0000, v47
	v_mfma_f32_4x4x1_16b_f32 v[4:7], v22, v88, v[4:7]
	v_mfma_f32_4x4x1_16b_f32 v[8:11], v22, v96, v[8:11]
	v_lshlrev_b32_e32 v32, 16, v48
	v_mfma_f32_4x4x1_16b_f32 v[12:15], v26, v88, v[12:15]
	v_mfma_f32_4x4x1_16b_f32 v[16:19], v26, v96, v[16:19]
	v_and_b32_e32 v48, 0xffff0000, v48
	v_mfma_f32_4x4x1_16b_f32 v[4:7], v38, v89, v[4:7]
	v_mfma_f32_4x4x1_16b_f32 v[8:11], v38, v97, v[8:11]
	v_lshlrev_b32_e32 v33, 16, v49
	v_mfma_f32_4x4x1_16b_f32 v[12:15], v42, v89, v[12:15]
	v_mfma_f32_4x4x1_16b_f32 v[16:19], v42, v97, v[16:19]
	v_and_b32_e32 v49, 0xffff0000, v49
	v_mfma_f32_4x4x1_16b_f32 v[4:7], v23, v90, v[4:7]
	v_mfma_f32_4x4x1_16b_f32 v[8:11], v23, v98, v[8:11]
	v_lshlrev_b32_e32 v34, 16, v50
	v_mfma_f32_4x4x1_16b_f32 v[12:15], v27, v90, v[12:15]
	v_mfma_f32_4x4x1_16b_f32 v[16:19], v27, v98, v[16:19]
	v_and_b32_e32 v50, 0xffff0000, v50
	v_mfma_f32_4x4x1_16b_f32 v[4:7], v39, v91, v[4:7]
	v_mfma_f32_4x4x1_16b_f32 v[8:11], v39, v99, v[8:11]
	v_lshlrev_b32_e32 v35, 16, v51
	v_mfma_f32_4x4x1_16b_f32 v[12:15], v43, v91, v[12:15]
	v_mfma_f32_4x4x1_16b_f32 v[16:19], v43, v99, v[16:19]
	v_and_b32_e32 v51, 0xffff0000, v51
	s_add_i32 s1, s13, 6
	s_and_b32 s1, s1, 15
	s_lshl_b32 s1, s1, 8
	s_add_u32 s10, s6, s1
	s_addc_u32 s11, s7, 0
	global_load_dwordx4 v[36:39], v2, s[10:11]
	global_load_dwordx4 v[40:43], v116, s[10:11]
	s_add_i32 s1, s13, 2
	s_and_b32 s1, s1, 15
	s_lshl_b32 s1, s1, 12
	v_add_u32_e32 v117, s1, v3
	ds_read_b128 v[84:87], v117 offset:0
	ds_read_b128 v[88:91], v117 offset:1024
	ds_read_b128 v[92:95], v117 offset:2048
	ds_read_b128 v[96:99], v117 offset:3072
	s_waitcnt vmcnt(8)
	s_waitcnt lgkmcnt(4)
	v_mfma_f32_4x4x1_16b_f32 v[4:7], v28, v100, v[4:7]
	v_mfma_f32_4x4x1_16b_f32 v[8:11], v28, v108, v[8:11]
	v_lshlrev_b32_e32 v20, 16, v52
	v_mfma_f32_4x4x1_16b_f32 v[12:15], v32, v100, v[12:15]
	v_mfma_f32_4x4x1_16b_f32 v[16:19], v32, v108, v[16:19]
	v_and_b32_e32 v52, 0xffff0000, v52
	v_mfma_f32_4x4x1_16b_f32 v[4:7], v44, v101, v[4:7]
	v_mfma_f32_4x4x1_16b_f32 v[8:11], v44, v109, v[8:11]
	v_lshlrev_b32_e32 v21, 16, v53
	v_mfma_f32_4x4x1_16b_f32 v[12:15], v48, v101, v[12:15]
	v_mfma_f32_4x4x1_16b_f32 v[16:19], v48, v109, v[16:19]
	v_and_b32_e32 v53, 0xffff0000, v53
	v_mfma_f32_4x4x1_16b_f32 v[4:7], v29, v102, v[4:7]
	v_mfma_f32_4x4x1_16b_f32 v[8:11], v29, v110, v[8:11]
	v_lshlrev_b32_e32 v22, 16, v54
	v_mfma_f32_4x4x1_16b_f32 v[12:15], v33, v102, v[12:15]
	v_mfma_f32_4x4x1_16b_f32 v[16:19], v33, v110, v[16:19]
	v_and_b32_e32 v54, 0xffff0000, v54
	v_mfma_f32_4x4x1_16b_f32 v[4:7], v45, v103, v[4:7]
	v_mfma_f32_4x4x1_16b_f32 v[8:11], v45, v111, v[8:11]
	v_lshlrev_b32_e32 v23, 16, v55
	v_mfma_f32_4x4x1_16b_f32 v[12:15], v49, v103, v[12:15]
	v_mfma_f32_4x4x1_16b_f32 v[16:19], v49, v111, v[16:19]
	v_and_b32_e32 v55, 0xffff0000, v55
	v_mfma_f32_4x4x1_16b_f32 v[4:7], v30, v104, v[4:7]
	v_mfma_f32_4x4x1_16b_f32 v[8:11], v30, v112, v[8:11]
	v_lshlrev_b32_e32 v24, 16, v56
	v_mfma_f32_4x4x1_16b_f32 v[12:15], v34, v104, v[12:15]
	v_mfma_f32_4x4x1_16b_f32 v[16:19], v34, v112, v[16:19]
	v_and_b32_e32 v56, 0xffff0000, v56
	v_mfma_f32_4x4x1_16b_f32 v[4:7], v46, v105, v[4:7]
	v_mfma_f32_4x4x1_16b_f32 v[8:11], v46, v113, v[8:11]
	v_lshlrev_b32_e32 v25, 16, v57
	v_mfma_f32_4x4x1_16b_f32 v[12:15], v50, v105, v[12:15]
	v_mfma_f32_4x4x1_16b_f32 v[16:19], v50, v113, v[16:19]
	v_and_b32_e32 v57, 0xffff0000, v57
	v_mfma_f32_4x4x1_16b_f32 v[4:7], v31, v106, v[4:7]
	v_mfma_f32_4x4x1_16b_f32 v[8:11], v31, v114, v[8:11]
	v_lshlrev_b32_e32 v26, 16, v58
	v_mfma_f32_4x4x1_16b_f32 v[12:15], v35, v106, v[12:15]
	v_mfma_f32_4x4x1_16b_f32 v[16:19], v35, v114, v[16:19]
	v_and_b32_e32 v58, 0xffff0000, v58
	v_mfma_f32_4x4x1_16b_f32 v[4:7], v47, v107, v[4:7]
	v_mfma_f32_4x4x1_16b_f32 v[8:11], v47, v115, v[8:11]
	v_lshlrev_b32_e32 v27, 16, v59
	v_mfma_f32_4x4x1_16b_f32 v[12:15], v51, v107, v[12:15]
	v_mfma_f32_4x4x1_16b_f32 v[16:19], v51, v115, v[16:19]
	v_and_b32_e32 v59, 0xffff0000, v59
	s_add_i32 s1, s13, 7
	s_and_b32 s1, s1, 15
	s_lshl_b32 s1, s1, 8
	s_add_u32 s10, s6, s1
	s_addc_u32 s11, s7, 0
	global_load_dwordx4 v[44:47], v2, s[10:11]
	global_load_dwordx4 v[48:51], v116, s[10:11]
	s_add_i32 s1, s13, 3
	s_and_b32 s1, s1, 15
	s_lshl_b32 s1, s1, 12
	v_add_u32_e32 v117, s1, v3
	ds_read_b128 v[100:103], v117 offset:0
	ds_read_b128 v[104:107], v117 offset:1024
	ds_read_b128 v[108:111], v117 offset:2048
	ds_read_b128 v[112:115], v117 offset:3072
	s_waitcnt vmcnt(8)
	s_waitcnt lgkmcnt(4)
; __global__ void __launch_bounds__(NWAVES * 64, 2) fwd_megakernel(Args args) {
;     ...
;                 for (int q = 0; q < 4; ++q) { float d = 0.f;
; #pragma unroll
;                     for (int jj = 0; jj < 4; ++jj) { const u32x4 w = pw[q][jj];
;                         d += __uint_as_float(w.x << 16) * wreg[8 * jj + 0] + __uint_as_float(w.x & 0xffff0000u) * wreg[8 * jj + 1] + __uint_as_float(w.y << 16) * wreg[8 * jj + 2] + __uint_as_float(w.y & 0xffff0000u) * wreg[8 * jj + 3]
;                            + __uint_as_float(w.z << 16) * wreg[8 * jj + 4] + __uint_as_float(w.z & 0xffff0000u) * wreg[8 * jj + 5] + __uint_as_float(w.w << 16) * wreg[8 * jj + 6] + __uint_as_float(w.w & 0xffff0000u) * wreg[8 * jj + 7]; }
	v_mfma_f32_4x4x1_16b_f32 v[4:7], v20, v84, v[4:7]
	v_mfma_f32_4x4x1_16b_f32 v[8:11], v20, v92, v[8:11]
	v_lshlrev_b32_e32 v28, 16, v60
	v_mfma_f32_4x4x1_16b_f32 v[12:15], v24, v84, v[12:15]
	v_mfma_f32_4x4x1_16b_f32 v[16:19], v24, v92, v[16:19]
	v_and_b32_e32 v60, 0xffff0000, v60
	v_mfma_f32_4x4x1_16b_f32 v[4:7], v52, v85, v[4:7]
	v_mfma_f32_4x4x1_16b_f32 v[8:11], v52, v93, v[8:11]
	v_lshlrev_b32_e32 v29, 16, v61
	v_mfma_f32_4x4x1_16b_f32 v[12:15], v56, v85, v[12:15]
	v_mfma_f32_4x4x1_16b_f32 v[16:19], v56, v93, v[16:19]
	v_and_b32_e32 v61, 0xffff0000, v61
	v_mfma_f32_4x4x1_16b_f32 v[4:7], v21, v86, v[4:7]
	v_mfma_f32_4x4x1_16b_f32 v[8:11], v21, v94, v[8:11]
	v_lshlrev_b32_e32 v30, 16, v62
	v_mfma_f32_4x4x1_16b_f32 v[12:15], v25, v86, v[12:15]
	v_mfma_f32_4x4x1_16b_f32 v[16:19], v25, v94, v[16:19]
	v_and_b32_e32 v62, 0xffff0000, v62
	v_mfma_f32_4x4x1_16b_f32 v[4:7], v53, v87, v[4:7]
	v_mfma_f32_4x4x1_16b_f32 v[8:11], v53, v95, v[8:11]
	v_lshlrev_b32_e32 v31, 16, v63
	v_mfma_f32_4x4x1_16b_f32 v[12:15], v57, v87, v[12:15]
	v_mfma_f32_4x4x1_16b_f32 v[16:19], v57, v95, v[16:19]
	v_and_b32_e32 v63, 0xffff0000, v63
	v_mfma_f32_4x4x1_16b_f32 v[4:7], v22, v88, v[4:7]
	v_mfma_f32_4x4x1_16b_f32 v[8:11], v22, v96, v[8:11]
	v_lshlrev_b32_e32 v32, 16, v64
	v_mfma_f32_4x4x1_16b_f32 v[12:15], v26, v88, v[12:15]
	v_mfma_f32_4x4x1_16b_f32 v[16:19], v26, v96, v[16:19]
	v_and_b32_e32 v64, 0xffff0000, v64
	v_mfma_f32_4x4x1_16b_f32 v[4:7], v54, v89, v[4:7]
	v_mfma_f32_4x4x1_16b_f32 v[8:11], v54, v97, v[8:11]
	v_lshlrev_b32_e32 v33, 16, v65
	v_mfma_f32_4x4x1_16b_f32 v[12:15], v58, v89, v[12:15]
	v_mfma_f32_4x4x1_16b_f32 v[16:19], v58, v97, v[16:19]
	v_and_b32_e32 v65, 0xffff0000, v65
	v_mfma_f32_4x4x1_16b_f32 v[4:7], v23, v90, v[4:7]
	v_mfma_f32_4x4x1_16b_f32 v[8:11], v23, v98, v[8:11]
	v_lshlrev_b32_e32 v34, 16, v66
	v_mfma_f32_4x4x1_16b_f32 v[12:15], v27, v90, v[12:15]
	v_mfma_f32_4x4x1_16b_f32 v[16:19], v27, v98, v[16:19]
	v_and_b32_e32 v66, 0xffff0000, v66
	v_mfma_f32_4x4x1_16b_f32 v[4:7], v55, v91, v[4:7]
	v_mfma_f32_4x4x1_16b_f32 v[8:11], v55, v99, v[8:11]
	v_lshlrev_b32_e32 v35, 16, v67
	v_mfma_f32_4x4x1_16b_f32 v[12:15], v59, v91, v[12:15]
	v_mfma_f32_4x4x1_16b_f32 v[16:19], v59, v99, v[16:19]
	v_and_b32_e32 v67, 0xffff0000, v67
	s_add_i32 s1, s13, 8
	s_and_b32 s1, s1, 15
	s_lshl_b32 s1, s1, 8
	s_add_u32 s10, s6, s1
	s_addc_u32 s11, s7, 0
	global_load_dwordx4 v[52:55], v2, s[10:11]
	global_load_dwordx4 v[56:59], v116, s[10:11]
	s_add_i32 s1, s13, 4
	s_and_b32 s1, s1, 15
	s_lshl_b32 s1, s1, 12
	v_add_u32_e32 v117, s1, v3
	ds_read_b128 v[84:87], v117 offset:0
	ds_read_b128 v[88:91], v117 offset:1024
	ds_read_b128 v[92:95], v117 offset:2048
	ds_read_b128 v[96:99], v117 offset:3072
	s_waitcnt vmcnt(8)
	s_waitcnt lgkmcnt(4)
	v_mfma_f32_4x4x1_16b_f32 v[4:7], v28, v100, v[4:7]
	v_mfma_f32_4x4x1_16b_f32 v[8:11], v28, v108, v[8:11]
	v_lshlrev_b32_e32 v20, 16, v68
	v_mfma_f32_4x4x1_16b_f32 v[12:15], v32, v100, v[12:15]
	v_mfma_f32_4x4x1_16b_f32 v[16:19], v32, v108, v[16:19]
	v_and_b32_e32 v68, 0xffff0000, v68
	v_mfma_f32_4x4x1_16b_f32 v[4:7], v60, v101, v[4:7]
	v_mfma_f32_4x4x1_16b_f32 v[8:11], v60, v109, v[8:11]
	v_lshlrev_b32_e32 v21, 16, v69
	v_mfma_f32_4x4x1_16b_f32 v[12:15], v64, v101, v[12:15]
	v_mfma_f32_4x4x1_16b_f32 v[16:19], v64, v109, v[16:19]
	v_and_b32_e32 v69, 0xffff0000, v69
	v_mfma_f32_4x4x1_16b_f32 v[4:7], v29, v102, v[4:7]
	v_mfma_f32_4x4x1_16b_f32 v[8:11], v29, v110, v[8:11]
	v_lshlrev_b32_e32 v22, 16, v70
	v_mfma_f32_4x4x1_16b_f32 v[12:15], v33, v102, v[12:15]
	v_mfma_f32_4x4x1_16b_f32 v[16:19], v33, v110, v[16:19]
	v_and_b32_e32 v70, 0xffff0000, v70
	v_mfma_f32_4x4x1_16b_f32 v[4:7], v61, v103, v[4:7]
	v_mfma_f32_4x4x1_16b_f32 v[8:11], v61, v111, v[8:11]
	v_lshlrev_b32_e32 v23, 16, v71
	v_mfma_f32_4x4x1_16b_f32 v[12:15], v65, v103, v[12:15]
	v_mfma_f32_4x4x1_16b_f32 v[16:19], v65, v111, v[16:19]
	v_and_b32_e32 v71, 0xffff0000, v71
	v_mfma_f32_4x4x1_16b_f32 v[4:7], v30, v104, v[4:7]
	v_mfma_f32_4x4x1_16b_f32 v[8:11], v30, v112, v[8:11]
	v_lshlrev_b32_e32 v24, 16, v72
	v_mfma_f32_4x4x1_16b_f32 v[12:15], v34, v104, v[12:15]
	v_mfma_f32_4x4x1_16b_f32 v[16:19], v34, v112, v[16:19]
	v_and_b32_e32 v72, 0xffff0000, v72
	v_mfma_f32_4x4x1_16b_f32 v[4:7], v62, v105, v[4:7]
	v_mfma_f32_4x4x1_16b_f32 v[8:11], v62, v113, v[8:11]
	v_lshlrev_b32_e32 v25, 16, v73
	v_mfma_f32_4x4x1_16b_f32 v[12:15], v66, v105, v[12:15]
	v_mfma_f32_4x4x1_16b_f32 v[16:19], v66, v113, v[16:19]
	v_and_b32_e32 v73, 0xffff0000, v73
	v_mfma_f32_4x4x1_16b_f32 v[4:7], v31, v106, v[4:7]
	v_mfma_f32_4x4x1_16b_f32 v[8:11], v31, v114, v[8:11]
	v_lshlrev_b32_e32 v26, 16, v74
	v_mfma_f32_4x4x1_16b_f32 v[12:15], v35, v106, v[12:15]
	v_mfma_f32_4x4x1_16b_f32 v[16:19], v35, v114, v[16:19]
	v_and_b32_e32 v74, 0xffff0000, v74
	v_mfma_f32_4x4x1_16b_f32 v[4:7], v63, v107, v[4:7]
	v_mfma_f32_4x4x1_16b_f32 v[8:11], v63, v115, v[8:11]
	v_lshlrev_b32_e32 v27, 16, v75
	v_mfma_f32_4x4x1_16b_f32 v[12:15], v67, v107, v[12:15]
	v_mfma_f32_4x4x1_16b_f32 v[16:19], v67, v115, v[16:19]
	v_and_b32_e32 v75, 0xffff0000, v75
	s_add_i32 s1, s13, 9
	s_and_b32 s1, s1, 15
	s_lshl_b32 s1, s1, 8
	s_add_u32 s10, s6, s1
	s_addc_u32 s11, s7, 0
	global_load_dwordx4 v[60:63], v2, s[10:11]
	global_load_dwordx4 v[64:67], v116, s[10:11]
	s_add_i32 s1, s13, 5
	s_and_b32 s1, s1, 15
	s_lshl_b32 s1, s1, 12
	v_add_u32_e32 v117, s1, v3
	ds_read_b128 v[100:103], v117 offset:0
	ds_read_b128 v[104:107], v117 offset:1024
	ds_read_b128 v[108:111], v117 offset:2048
	ds_read_b128 v[112:115], v117 offset:3072
	s_waitcnt vmcnt(8)
	s_waitcnt lgkmcnt(4)
; __global__ void __launch_bounds__(NWAVES * 64, 2) fwd_megakernel(Args args) {
;     ...
;                 for (int q = 0; q < 4; ++q) { float d = 0.f;
; #pragma unroll
;                     for (int jj = 0; jj < 4; ++jj) { const u32x4 w = pw[q][jj];
;                         d += __uint_as_float(w.x << 16) * wreg[8 * jj + 0] + __uint_as_float(w.x & 0xffff0000u) * wreg[8 * jj + 1] + __uint_as_float(w.y << 16) * wreg[8 * jj + 2] + __uint_as_float(w.y & 0xffff0000u) * wreg[8 * jj + 3]
;                            + __uint_as_float(w.z << 16) * wreg[8 * jj + 4] + __uint_as_float(w.z & 0xffff0000u) * wreg[8 * jj + 5] + __uint_as_float(w.w << 16) * wreg[8 * jj + 6] + __uint_as_float(w.w & 0xffff0000u) * wreg[8 * jj + 7]; }
	v_mfma_f32_4x4x1_16b_f32 v[4:7], v20, v84, v[4:7]
	v_mfma_f32_4x4x1_16b_f32 v[8:11], v20, v92, v[8:11]
	v_lshlrev_b32_e32 v28, 16, v76
	v_mfma_f32_4x4x1_16b_f32 v[12:15], v24, v84, v[12:15]
	v_mfma_f32_4x4x1_16b_f32 v[16:19], v24, v92, v[16:19]
	v_and_b32_e32 v76, 0xffff0000, v76
	v_mfma_f32_4x4x1_16b_f32 v[4:7], v68, v85, v[4:7]
	v_mfma_f32_4x4x1_16b_f32 v[8:11], v68, v93, v[8:11]
	v_lshlrev_b32_e32 v29, 16, v77
	v_mfma_f32_4x4x1_16b_f32 v[12:15], v72, v85, v[12:15]
	v_mfma_f32_4x4x1_16b_f32 v[16:19], v72, v93, v[16:19]
	v_and_b32_e32 v77, 0xffff0000, v77
	v_mfma_f32_4x4x1_16b_f32 v[4:7], v21, v86, v[4:7]
	v_mfma_f32_4x4x1_16b_f32 v[8:11], v21, v94, v[8:11]
	v_lshlrev_b32_e32 v30, 16, v78
	v_mfma_f32_4x4x1_16b_f32 v[12:15], v25, v86, v[12:15]
	v_mfma_f32_4x4x1_16b_f32 v[16:19], v25, v94, v[16:19]
	v_and_b32_e32 v78, 0xffff0000, v78
	v_mfma_f32_4x4x1_16b_f32 v[4:7], v69, v87, v[4:7]
	v_mfma_f32_4x4x1_16b_f32 v[8:11], v69, v95, v[8:11]
	v_lshlrev_b32_e32 v31, 16, v79
	v_mfma_f32_4x4x1_16b_f32 v[12:15], v73, v87, v[12:15]
	v_mfma_f32_4x4x1_16b_f32 v[16:19], v73, v95, v[16:19]
	v_and_b32_e32 v79, 0xffff0000, v79
	v_mfma_f32_4x4x1_16b_f32 v[4:7], v22, v88, v[4:7]
	v_mfma_f32_4x4x1_16b_f32 v[8:11], v22, v96, v[8:11]
	v_lshlrev_b32_e32 v32, 16, v80
	v_mfma_f32_4x4x1_16b_f32 v[12:15], v26, v88, v[12:15]
	v_mfma_f32_4x4x1_16b_f32 v[16:19], v26, v96, v[16:19]
	v_and_b32_e32 v80, 0xffff0000, v80
	v_mfma_f32_4x4x1_16b_f32 v[4:7], v70, v89, v[4:7]
	v_mfma_f32_4x4x1_16b_f32 v[8:11], v70, v97, v[8:11]
	v_lshlrev_b32_e32 v33, 16, v81
	v_mfma_f32_4x4x1_16b_f32 v[12:15], v74, v89, v[12:15]
	v_mfma_f32_4x4x1_16b_f32 v[16:19], v74, v97, v[16:19]
	v_and_b32_e32 v81, 0xffff0000, v81
	v_mfma_f32_4x4x1_16b_f32 v[4:7], v23, v90, v[4:7]
	v_mfma_f32_4x4x1_16b_f32 v[8:11], v23, v98, v[8:11]
	v_lshlrev_b32_e32 v34, 16, v82
	v_mfma_f32_4x4x1_16b_f32 v[12:15], v27, v90, v[12:15]
	v_mfma_f32_4x4x1_16b_f32 v[16:19], v27, v98, v[16:19]
	v_and_b32_e32 v82, 0xffff0000, v82
	v_mfma_f32_4x4x1_16b_f32 v[4:7], v71, v91, v[4:7]
	v_mfma_f32_4x4x1_16b_f32 v[8:11], v71, v99, v[8:11]
	v_lshlrev_b32_e32 v35, 16, v83
	v_mfma_f32_4x4x1_16b_f32 v[12:15], v75, v91, v[12:15]
	v_mfma_f32_4x4x1_16b_f32 v[16:19], v75, v99, v[16:19]
	v_and_b32_e32 v83, 0xffff0000, v83
	s_add_i32 s1, s13, 10
	s_and_b32 s1, s1, 15
	s_lshl_b32 s1, s1, 8
	s_add_u32 s10, s6, s1
	s_addc_u32 s11, s7, 0
	global_load_dwordx4 v[68:71], v2, s[10:11]
	global_load_dwordx4 v[72:75], v116, s[10:11]
	s_add_i32 s1, s13, 6
	s_and_b32 s1, s1, 15
	s_lshl_b32 s1, s1, 12
	v_add_u32_e32 v117, s1, v3
	ds_read_b128 v[84:87], v117 offset:0
	ds_read_b128 v[88:91], v117 offset:1024
	ds_read_b128 v[92:95], v117 offset:2048
	ds_read_b128 v[96:99], v117 offset:3072
	s_waitcnt vmcnt(8)
	s_waitcnt lgkmcnt(4)
	v_mfma_f32_4x4x1_16b_f32 v[4:7], v28, v100, v[4:7]
	v_mfma_f32_4x4x1_16b_f32 v[8:11], v28, v108, v[8:11]
	v_lshlrev_b32_e32 v20, 16, v36
	v_mfma_f32_4x4x1_16b_f32 v[12:15], v32, v100, v[12:15]
	v_mfma_f32_4x4x1_16b_f32 v[16:19], v32, v108, v[16:19]
	v_and_b32_e32 v36, 0xffff0000, v36
	v_mfma_f32_4x4x1_16b_f32 v[4:7], v76, v101, v[4:7]
	v_mfma_f32_4x4x1_16b_f32 v[8:11], v76, v109, v[8:11]
	v_lshlrev_b32_e32 v21, 16, v37
	v_mfma_f32_4x4x1_16b_f32 v[12:15], v80, v101, v[12:15]
	v_mfma_f32_4x4x1_16b_f32 v[16:19], v80, v109, v[16:19]
	v_and_b32_e32 v37, 0xffff0000, v37
	v_mfma_f32_4x4x1_16b_f32 v[4:7], v29, v102, v[4:7]
	v_mfma_f32_4x4x1_16b_f32 v[8:11], v29, v110, v[8:11]
	v_lshlrev_b32_e32 v22, 16, v38
	v_mfma_f32_4x4x1_16b_f32 v[12:15], v33, v102, v[12:15]
	v_mfma_f32_4x4x1_16b_f32 v[16:19], v33, v110, v[16:19]
	v_and_b32_e32 v38, 0xffff0000, v38
	v_mfma_f32_4x4x1_16b_f32 v[4:7], v77, v103, v[4:7]
	v_mfma_f32_4x4x1_16b_f32 v[8:11], v77, v111, v[8:11]
	v_lshlrev_b32_e32 v23, 16, v39
	v_mfma_f32_4x4x1_16b_f32 v[12:15], v81, v103, v[12:15]
	v_mfma_f32_4x4x1_16b_f32 v[16:19], v81, v111, v[16:19]
	v_and_b32_e32 v39, 0xffff0000, v39
	v_mfma_f32_4x4x1_16b_f32 v[4:7], v30, v104, v[4:7]
	v_mfma_f32_4x4x1_16b_f32 v[8:11], v30, v112, v[8:11]
	v_lshlrev_b32_e32 v24, 16, v40
	v_mfma_f32_4x4x1_16b_f32 v[12:15], v34, v104, v[12:15]
	v_mfma_f32_4x4x1_16b_f32 v[16:19], v34, v112, v[16:19]
	v_and_b32_e32 v40, 0xffff0000, v40
	v_mfma_f32_4x4x1_16b_f32 v[4:7], v78, v105, v[4:7]
	v_mfma_f32_4x4x1_16b_f32 v[8:11], v78, v113, v[8:11]
	v_lshlrev_b32_e32 v25, 16, v41
	v_mfma_f32_4x4x1_16b_f32 v[12:15], v82, v105, v[12:15]
	v_mfma_f32_4x4x1_16b_f32 v[16:19], v82, v113, v[16:19]
	v_and_b32_e32 v41, 0xffff0000, v41
	v_mfma_f32_4x4x1_16b_f32 v[4:7], v31, v106, v[4:7]
	v_mfma_f32_4x4x1_16b_f32 v[8:11], v31, v114, v[8:11]
	v_lshlrev_b32_e32 v26, 16, v42
	v_mfma_f32_4x4x1_16b_f32 v[12:15], v35, v106, v[12:15]
	v_mfma_f32_4x4x1_16b_f32 v[16:19], v35, v114, v[16:19]
	v_and_b32_e32 v42, 0xffff0000, v42
	v_mfma_f32_4x4x1_16b_f32 v[4:7], v79, v107, v[4:7]
	v_mfma_f32_4x4x1_16b_f32 v[8:11], v79, v115, v[8:11]
	v_lshlrev_b32_e32 v27, 16, v43
	v_mfma_f32_4x4x1_16b_f32 v[12:15], v83, v107, v[12:15]
	v_mfma_f32_4x4x1_16b_f32 v[16:19], v83, v115, v[16:19]
	v_and_b32_e32 v43, 0xffff0000, v43
	s_add_i32 s1, s13, 11
	s_and_b32 s1, s1, 15
	s_lshl_b32 s1, s1, 8
	s_add_u32 s10, s6, s1
	s_addc_u32 s11, s7, 0
	global_load_dwordx4 v[76:79], v2, s[10:11]
	global_load_dwordx4 v[80:83], v116, s[10:11]
	s_add_i32 s1, s13, 7
	s_and_b32 s1, s1, 15
	s_lshl_b32 s1, s1, 12
	v_add_u32_e32 v117, s1, v3
	ds_read_b128 v[100:103], v117 offset:0
	ds_read_b128 v[104:107], v117 offset:1024
	ds_read_b128 v[108:111], v117 offset:2048
	ds_read_b128 v[112:115], v117 offset:3072
	s_waitcnt vmcnt(8)
	s_waitcnt lgkmcnt(4)
; __global__ void __launch_bounds__(NWAVES * 64, 2) fwd_megakernel(Args args) {
;     ...
;                 for (int q = 0; q < 4; ++q) { float d = 0.f;
; #pragma unroll
;                     for (int jj = 0; jj < 4; ++jj) { const u32x4 w = pw[q][jj];
;                         d += __uint_as_float(w.x << 16) * wreg[8 * jj + 0] + __uint_as_float(w.x & 0xffff0000u) * wreg[8 * jj + 1] + __uint_as_float(w.y << 16) * wreg[8 * jj + 2] + __uint_as_float(w.y & 0xffff0000u) * wreg[8 * jj + 3]
;                            + __uint_as_float(w.z << 16) * wreg[8 * jj + 4] + __uint_as_float(w.z & 0xffff0000u) * wreg[8 * jj + 5] + __uint_as_float(w.w << 16) * wreg[8 * jj + 6] + __uint_as_float(w.w & 0xffff0000u) * wreg[8 * jj + 7]; }
	v_mfma_f32_4x4x1_16b_f32 v[4:7], v20, v84, v[4:7]
	v_mfma_f32_4x4x1_16b_f32 v[8:11], v20, v92, v[8:11]
	v_lshlrev_b32_e32 v28, 16, v44
	v_mfma_f32_4x4x1_16b_f32 v[12:15], v24, v84, v[12:15]
	v_mfma_f32_4x4x1_16b_f32 v[16:19], v24, v92, v[16:19]
	v_and_b32_e32 v44, 0xffff0000, v44
	v_mfma_f32_4x4x1_16b_f32 v[4:7], v36, v85, v[4:7]
	v_mfma_f32_4x4x1_16b_f32 v[8:11], v36, v93, v[8:11]
	v_lshlrev_b32_e32 v29, 16, v45
	v_mfma_f32_4x4x1_16b_f32 v[12:15], v40, v85, v[12:15]
	v_mfma_f32_4x4x1_16b_f32 v[16:19], v40, v93, v[16:19]
	v_and_b32_e32 v45, 0xffff0000, v45
	v_mfma_f32_4x4x1_16b_f32 v[4:7], v21, v86, v[4:7]
	v_mfma_f32_4x4x1_16b_f32 v[8:11], v21, v94, v[8:11]
	v_lshlrev_b32_e32 v30, 16, v46
	v_mfma_f32_4x4x1_16b_f32 v[12:15], v25, v86, v[12:15]
	v_mfma_f32_4x4x1_16b_f32 v[16:19], v25, v94, v[16:19]
	v_and_b32_e32 v46, 0xffff0000, v46
	v_mfma_f32_4x4x1_16b_f32 v[4:7], v37, v87, v[4:7]
	v_mfma_f32_4x4x1_16b_f32 v[8:11], v37, v95, v[8:11]
	v_lshlrev_b32_e32 v31, 16, v47
	v_mfma_f32_4x4x1_16b_f32 v[12:15], v41, v87, v[12:15]
	v_mfma_f32_4x4x1_16b_f32 v[16:19], v41, v95, v[16:19]
	v_and_b32_e32 v47, 0xffff0000, v47
	v_mfma_f32_4x4x1_16b_f32 v[4:7], v22, v88, v[4:7]
	v_mfma_f32_4x4x1_16b_f32 v[8:11], v22, v96, v[8:11]
	v_lshlrev_b32_e32 v32, 16, v48
	v_mfma_f32_4x4x1_16b_f32 v[12:15], v26, v88, v[12:15]
	v_mfma_f32_4x4x1_16b_f32 v[16:19], v26, v96, v[16:19]
	v_and_b32_e32 v48, 0xffff0000, v48
	v_mfma_f32_4x4x1_16b_f32 v[4:7], v38, v89, v[4:7]
	v_mfma_f32_4x4x1_16b_f32 v[8:11], v38, v97, v[8:11]
	v_lshlrev_b32_e32 v33, 16, v49
	v_mfma_f32_4x4x1_16b_f32 v[12:15], v42, v89, v[12:15]
	v_mfma_f32_4x4x1_16b_f32 v[16:19], v42, v97, v[16:19]
	v_and_b32_e32 v49, 0xffff0000, v49
	v_mfma_f32_4x4x1_16b_f32 v[4:7], v23, v90, v[4:7]
	v_mfma_f32_4x4x1_16b_f32 v[8:11], v23, v98, v[8:11]
	v_lshlrev_b32_e32 v34, 16, v50
	v_mfma_f32_4x4x1_16b_f32 v[12:15], v27, v90, v[12:15]
	v_mfma_f32_4x4x1_16b_f32 v[16:19], v27, v98, v[16:19]
	v_and_b32_e32 v50, 0xffff0000, v50
	v_mfma_f32_4x4x1_16b_f32 v[4:7], v39, v91, v[4:7]
	v_mfma_f32_4x4x1_16b_f32 v[8:11], v39, v99, v[8:11]
	v_lshlrev_b32_e32 v35, 16, v51
	v_mfma_f32_4x4x1_16b_f32 v[12:15], v43, v91, v[12:15]
	v_mfma_f32_4x4x1_16b_f32 v[16:19], v43, v99, v[16:19]
	v_and_b32_e32 v51, 0xffff0000, v51
	s_add_i32 s1, s13, 12
	s_and_b32 s1, s1, 15
	s_lshl_b32 s1, s1, 8
	s_add_u32 s10, s6, s1
	s_addc_u32 s11, s7, 0
	global_load_dwordx4 v[36:39], v2, s[10:11]
	global_load_dwordx4 v[40:43], v116, s[10:11]
	s_add_i32 s1, s13, 8
	s_and_b32 s1, s1, 15
	s_lshl_b32 s1, s1, 12
	v_add_u32_e32 v117, s1, v3
	ds_read_b128 v[84:87], v117 offset:0
	ds_read_b128 v[88:91], v117 offset:1024
	ds_read_b128 v[92:95], v117 offset:2048
	ds_read_b128 v[96:99], v117 offset:3072
	s_waitcnt vmcnt(8)
	s_waitcnt lgkmcnt(4)
	v_mfma_f32_4x4x1_16b_f32 v[4:7], v28, v100, v[4:7]
	v_mfma_f32_4x4x1_16b_f32 v[8:11], v28, v108, v[8:11]
	v_lshlrev_b32_e32 v20, 16, v52
	v_mfma_f32_4x4x1_16b_f32 v[12:15], v32, v100, v[12:15]
	v_mfma_f32_4x4x1_16b_f32 v[16:19], v32, v108, v[16:19]
	v_and_b32_e32 v52, 0xffff0000, v52
	v_mfma_f32_4x4x1_16b_f32 v[4:7], v44, v101, v[4:7]
	v_mfma_f32_4x4x1_16b_f32 v[8:11], v44, v109, v[8:11]
	v_lshlrev_b32_e32 v21, 16, v53
	v_mfma_f32_4x4x1_16b_f32 v[12:15], v48, v101, v[12:15]
	v_mfma_f32_4x4x1_16b_f32 v[16:19], v48, v109, v[16:19]
	v_and_b32_e32 v53, 0xffff0000, v53
	v_mfma_f32_4x4x1_16b_f32 v[4:7], v29, v102, v[4:7]
	v_mfma_f32_4x4x1_16b_f32 v[8:11], v29, v110, v[8:11]
	v_lshlrev_b32_e32 v22, 16, v54
	v_mfma_f32_4x4x1_16b_f32 v[12:15], v33, v102, v[12:15]
	v_mfma_f32_4x4x1_16b_f32 v[16:19], v33, v110, v[16:19]
	v_and_b32_e32 v54, 0xffff0000, v54
	v_mfma_f32_4x4x1_16b_f32 v[4:7], v45, v103, v[4:7]
	v_mfma_f32_4x4x1_16b_f32 v[8:11], v45, v111, v[8:11]
	v_lshlrev_b32_e32 v23, 16, v55
	v_mfma_f32_4x4x1_16b_f32 v[12:15], v49, v103, v[12:15]
	v_mfma_f32_4x4x1_16b_f32 v[16:19], v49, v111, v[16:19]
	v_and_b32_e32 v55, 0xffff0000, v55
	v_mfma_f32_4x4x1_16b_f32 v[4:7], v30, v104, v[4:7]
	v_mfma_f32_4x4x1_16b_f32 v[8:11], v30, v112, v[8:11]
	v_lshlrev_b32_e32 v24, 16, v56
	v_mfma_f32_4x4x1_16b_f32 v[12:15], v34, v104, v[12:15]
	v_mfma_f32_4x4x1_16b_f32 v[16:19], v34, v112, v[16:19]
	v_and_b32_e32 v56, 0xffff0000, v56
	v_mfma_f32_4x4x1_16b_f32 v[4:7], v46, v105, v[4:7]
	v_mfma_f32_4x4x1_16b_f32 v[8:11], v46, v113, v[8:11]
	v_lshlrev_b32_e32 v25, 16, v57
	v_mfma_f32_4x4x1_16b_f32 v[12:15], v50, v105, v[12:15]
	v_mfma_f32_4x4x1_16b_f32 v[16:19], v50, v113, v[16:19]
	v_and_b32_e32 v57, 0xffff0000, v57
	v_mfma_f32_4x4x1_16b_f32 v[4:7], v31, v106, v[4:7]
	v_mfma_f32_4x4x1_16b_f32 v[8:11], v31, v114, v[8:11]
	v_lshlrev_b32_e32 v26, 16, v58
	v_mfma_f32_4x4x1_16b_f32 v[12:15], v35, v106, v[12:15]
	v_mfma_f32_4x4x1_16b_f32 v[16:19], v35, v114, v[16:19]
	v_and_b32_e32 v58, 0xffff0000, v58
	v_mfma_f32_4x4x1_16b_f32 v[4:7], v47, v107, v[4:7]
	v_mfma_f32_4x4x1_16b_f32 v[8:11], v47, v115, v[8:11]
	v_lshlrev_b32_e32 v27, 16, v59
	v_mfma_f32_4x4x1_16b_f32 v[12:15], v51, v107, v[12:15]
	v_mfma_f32_4x4x1_16b_f32 v[16:19], v51, v115, v[16:19]
	v_and_b32_e32 v59, 0xffff0000, v59
	s_add_i32 s1, s13, 13
	s_and_b32 s1, s1, 15
	s_lshl_b32 s1, s1, 8
	s_add_u32 s10, s6, s1
	s_addc_u32 s11, s7, 0
	global_load_dwordx4 v[44:47], v2, s[10:11]
	global_load_dwordx4 v[48:51], v116, s[10:11]
	s_add_i32 s1, s13, 9
	s_and_b32 s1, s1, 15
	s_lshl_b32 s1, s1, 12
	v_add_u32_e32 v117, s1, v3
	ds_read_b128 v[100:103], v117 offset:0
	ds_read_b128 v[104:107], v117 offset:1024
	ds_read_b128 v[108:111], v117 offset:2048
	ds_read_b128 v[112:115], v117 offset:3072
	s_waitcnt vmcnt(8)
	s_waitcnt lgkmcnt(4)
; __global__ void __launch_bounds__(NWAVES * 64, 2) fwd_megakernel(Args args) {
;     ...
;                     for (int jj = 0; jj < 4; ++jj) pw[q][jj] = *(const u32x4*)(XB + (size_t)(m0 + q) * DM + 512 * jj + 8 * ln); }
; #pragma unroll
;                 for (int q = 0; q < 4; ++q) { float d = 0.f;
; #pragma unroll
;                     for (int jj = 0; jj < 4; ++jj) { const u32x4 w = pw[q][jj];
;                         d += __uint_as_float(w.x << 16) * wreg[8 * jj + 0] + __uint_as_float(w.x & 0xffff0000u) * wreg[8 * jj + 1] + __uint_as_float(w.y << 16) * wreg[8 * jj + 2] + __uint_as_float(w.y & 0xffff0000u) * wreg[8 * jj + 3]
;                            + __uint_as_float(w.z << 16) * wreg[8 * jj + 4] + __uint_as_float(w.z & 0xffff0000u) * wreg[8 * jj + 5] + __uint_as_float(w.w << 16) * wreg[8 * jj + 6] + __uint_as_float(w.w & 0xffff0000u) * wreg[8 * jj + 7]; }
	v_mfma_f32_4x4x1_16b_f32 v[4:7], v20, v84, v[4:7]
	v_mfma_f32_4x4x1_16b_f32 v[8:11], v20, v92, v[8:11]
	v_lshlrev_b32_e32 v28, 16, v60
	v_mfma_f32_4x4x1_16b_f32 v[12:15], v24, v84, v[12:15]
	v_mfma_f32_4x4x1_16b_f32 v[16:19], v24, v92, v[16:19]
	v_and_b32_e32 v60, 0xffff0000, v60
	v_mfma_f32_4x4x1_16b_f32 v[4:7], v52, v85, v[4:7]
	v_mfma_f32_4x4x1_16b_f32 v[8:11], v52, v93, v[8:11]
	v_lshlrev_b32_e32 v29, 16, v61
	v_mfma_f32_4x4x1_16b_f32 v[12:15], v56, v85, v[12:15]
	v_mfma_f32_4x4x1_16b_f32 v[16:19], v56, v93, v[16:19]
	v_and_b32_e32 v61, 0xffff0000, v61
	v_mfma_f32_4x4x1_16b_f32 v[4:7], v21, v86, v[4:7]
	v_mfma_f32_4x4x1_16b_f32 v[8:11], v21, v94, v[8:11]
	v_lshlrev_b32_e32 v30, 16, v62
	v_mfma_f32_4x4x1_16b_f32 v[12:15], v25, v86, v[12:15]
	v_mfma_f32_4x4x1_16b_f32 v[16:19], v25, v94, v[16:19]
	v_and_b32_e32 v62, 0xffff0000, v62
	v_mfma_f32_4x4x1_16b_f32 v[4:7], v53, v87, v[4:7]
	v_mfma_f32_4x4x1_16b_f32 v[8:11], v53, v95, v[8:11]
	v_lshlrev_b32_e32 v31, 16, v63
	v_mfma_f32_4x4x1_16b_f32 v[12:15], v57, v87, v[12:15]
	v_mfma_f32_4x4x1_16b_f32 v[16:19], v57, v95, v[16:19]
	v_and_b32_e32 v63, 0xffff0000, v63
	v_mfma_f32_4x4x1_16b_f32 v[4:7], v22, v88, v[4:7]
	v_mfma_f32_4x4x1_16b_f32 v[8:11], v22, v96, v[8:11]
	v_lshlrev_b32_e32 v32, 16, v64
	v_mfma_f32_4x4x1_16b_f32 v[12:15], v26, v88, v[12:15]
	v_mfma_f32_4x4x1_16b_f32 v[16:19], v26, v96, v[16:19]
	v_and_b32_e32 v64, 0xffff0000, v64
	v_mfma_f32_4x4x1_16b_f32 v[4:7], v54, v89, v[4:7]
	v_mfma_f32_4x4x1_16b_f32 v[8:11], v54, v97, v[8:11]
	v_lshlrev_b32_e32 v33, 16, v65
	v_mfma_f32_4x4x1_16b_f32 v[12:15], v58, v89, v[12:15]
	v_mfma_f32_4x4x1_16b_f32 v[16:19], v58, v97, v[16:19]
	v_and_b32_e32 v65, 0xffff0000, v65
	v_mfma_f32_4x4x1_16b_f32 v[4:7], v23, v90, v[4:7]
	v_mfma_f32_4x4x1_16b_f32 v[8:11], v23, v98, v[8:11]
	v_lshlrev_b32_e32 v34, 16, v66
	v_mfma_f32_4x4x1_16b_f32 v[12:15], v27, v90, v[12:15]
	v_mfma_f32_4x4x1_16b_f32 v[16:19], v27, v98, v[16:19]
	v_and_b32_e32 v66, 0xffff0000, v66
	v_mfma_f32_4x4x1_16b_f32 v[4:7], v55, v91, v[4:7]
	v_mfma_f32_4x4x1_16b_f32 v[8:11], v55, v99, v[8:11]
	v_lshlrev_b32_e32 v35, 16, v67
	v_mfma_f32_4x4x1_16b_f32 v[12:15], v59, v91, v[12:15]
	v_mfma_f32_4x4x1_16b_f32 v[16:19], v59, v99, v[16:19]
	v_and_b32_e32 v67, 0xffff0000, v67
	s_add_i32 s1, s13, 14
	s_and_b32 s1, s1, 15
	s_lshl_b32 s1, s1, 8
	s_add_u32 s10, s6, s1
	s_addc_u32 s11, s7, 0
	global_load_dwordx4 v[52:55], v2, s[10:11]
	global_load_dwordx4 v[56:59], v116, s[10:11]
	s_add_i32 s1, s13, 10
	s_and_b32 s1, s1, 15
	s_lshl_b32 s1, s1, 12
	v_add_u32_e32 v117, s1, v3
	ds_read_b128 v[84:87], v117 offset:0
	ds_read_b128 v[88:91], v117 offset:1024
	ds_read_b128 v[92:95], v117 offset:2048
	ds_read_b128 v[96:99], v117 offset:3072
	s_waitcnt vmcnt(8)
	s_waitcnt lgkmcnt(4)
	v_mfma_f32_4x4x1_16b_f32 v[4:7], v28, v100, v[4:7]
	v_mfma_f32_4x4x1_16b_f32 v[8:11], v28, v108, v[8:11]
	v_lshlrev_b32_e32 v20, 16, v68
	v_mfma_f32_4x4x1_16b_f32 v[12:15], v32, v100, v[12:15]
	v_mfma_f32_4x4x1_16b_f32 v[16:19], v32, v108, v[16:19]
	v_and_b32_e32 v68, 0xffff0000, v68
	v_mfma_f32_4x4x1_16b_f32 v[4:7], v60, v101, v[4:7]
	v_mfma_f32_4x4x1_16b_f32 v[8:11], v60, v109, v[8:11]
	v_lshlrev_b32_e32 v21, 16, v69
	v_mfma_f32_4x4x1_16b_f32 v[12:15], v64, v101, v[12:15]
	v_mfma_f32_4x4x1_16b_f32 v[16:19], v64, v109, v[16:19]
	v_and_b32_e32 v69, 0xffff0000, v69
	v_mfma_f32_4x4x1_16b_f32 v[4:7], v29, v102, v[4:7]
	v_mfma_f32_4x4x1_16b_f32 v[8:11], v29, v110, v[8:11]
	v_lshlrev_b32_e32 v22, 16, v70
	v_mfma_f32_4x4x1_16b_f32 v[12:15], v33, v102, v[12:15]
	v_mfma_f32_4x4x1_16b_f32 v[16:19], v33, v110, v[16:19]
	v_and_b32_e32 v70, 0xffff0000, v70
	v_mfma_f32_4x4x1_16b_f32 v[4:7], v61, v103, v[4:7]
	v_mfma_f32_4x4x1_16b_f32 v[8:11], v61, v111, v[8:11]
	v_lshlrev_b32_e32 v23, 16, v71
	v_mfma_f32_4x4x1_16b_f32 v[12:15], v65, v103, v[12:15]
	v_mfma_f32_4x4x1_16b_f32 v[16:19], v65, v111, v[16:19]
	v_and_b32_e32 v71, 0xffff0000, v71
	v_mfma_f32_4x4x1_16b_f32 v[4:7], v30, v104, v[4:7]
	v_mfma_f32_4x4x1_16b_f32 v[8:11], v30, v112, v[8:11]
	v_lshlrev_b32_e32 v24, 16, v72
	v_mfma_f32_4x4x1_16b_f32 v[12:15], v34, v104, v[12:15]
	v_mfma_f32_4x4x1_16b_f32 v[16:19], v34, v112, v[16:19]
	v_and_b32_e32 v72, 0xffff0000, v72
	v_mfma_f32_4x4x1_16b_f32 v[4:7], v62, v105, v[4:7]
	v_mfma_f32_4x4x1_16b_f32 v[8:11], v62, v113, v[8:11]
	v_lshlrev_b32_e32 v25, 16, v73
	v_mfma_f32_4x4x1_16b_f32 v[12:15], v66, v105, v[12:15]
	v_mfma_f32_4x4x1_16b_f32 v[16:19], v66, v113, v[16:19]
	v_and_b32_e32 v73, 0xffff0000, v73
	v_mfma_f32_4x4x1_16b_f32 v[4:7], v31, v106, v[4:7]
	v_mfma_f32_4x4x1_16b_f32 v[8:11], v31, v114, v[8:11]
	v_lshlrev_b32_e32 v26, 16, v74
	v_mfma_f32_4x4x1_16b_f32 v[12:15], v35, v106, v[12:15]
	v_mfma_f32_4x4x1_16b_f32 v[16:19], v35, v114, v[16:19]
	v_and_b32_e32 v74, 0xffff0000, v74
	v_mfma_f32_4x4x1_16b_f32 v[4:7], v63, v107, v[4:7]
	v_mfma_f32_4x4x1_16b_f32 v[8:11], v63, v115, v[8:11]
	v_lshlrev_b32_e32 v27, 16, v75
	v_mfma_f32_4x4x1_16b_f32 v[12:15], v67, v107, v[12:15]
	v_mfma_f32_4x4x1_16b_f32 v[16:19], v67, v115, v[16:19]
	v_and_b32_e32 v75, 0xffff0000, v75
	s_add_i32 s1, s13, 15
	s_and_b32 s1, s1, 15
	s_lshl_b32 s1, s1, 8
	s_add_u32 s10, s6, s1
	s_addc_u32 s11, s7, 0
	global_load_dwordx4 v[60:63], v2, s[10:11]
	global_load_dwordx4 v[64:67], v116, s[10:11]
	s_add_i32 s1, s13, 11
	s_and_b32 s1, s1, 15
	s_lshl_b32 s1, s1, 12
	v_add_u32_e32 v117, s1, v3
	ds_read_b128 v[100:103], v117 offset:0
	ds_read_b128 v[104:107], v117 offset:1024
	ds_read_b128 v[108:111], v117 offset:2048
	ds_read_b128 v[112:115], v117 offset:3072
	s_waitcnt vmcnt(8)
	s_waitcnt lgkmcnt(4)
; __global__ void __launch_bounds__(NWAVES * 64, 2) fwd_megakernel(Args args) {
;     ...
;                     for (int jj = 0; jj < 4; ++jj) pw[q][jj] = *(const u32x4*)(XB + (size_t)(m0 + q) * DM + 512 * jj + 8 * ln); }
; #pragma unroll
;                 for (int q = 0; q < 4; ++q) { float d = 0.f;
; #pragma unroll
;                     for (int jj = 0; jj < 4; ++jj) { const u32x4 w = pw[q][jj];
;                         d += __uint_as_float(w.x << 16) * wreg[8 * jj + 0] + __uint_as_float(w.x & 0xffff0000u) * wreg[8 * jj + 1] + __uint_as_float(w.y << 16) * wreg[8 * jj + 2] + __uint_as_float(w.y & 0xffff0000u) * wreg[8 * jj + 3]
;                            + __uint_as_float(w.z << 16) * wreg[8 * jj + 4] + __uint_as_float(w.z & 0xffff0000u) * wreg[8 * jj + 5] + __uint_as_float(w.w << 16) * wreg[8 * jj + 6] + __uint_as_float(w.w & 0xffff0000u) * wreg[8 * jj + 7]; }
	v_mfma_f32_4x4x1_16b_f32 v[4:7], v20, v84, v[4:7]
	v_mfma_f32_4x4x1_16b_f32 v[8:11], v20, v92, v[8:11]
	v_lshlrev_b32_e32 v28, 16, v76
	v_mfma_f32_4x4x1_16b_f32 v[12:15], v24, v84, v[12:15]
	v_mfma_f32_4x4x1_16b_f32 v[16:19], v24, v92, v[16:19]
	v_and_b32_e32 v76, 0xffff0000, v76
	v_mfma_f32_4x4x1_16b_f32 v[4:7], v68, v85, v[4:7]
	v_mfma_f32_4x4x1_16b_f32 v[8:11], v68, v93, v[8:11]
	v_lshlrev_b32_e32 v29, 16, v77
	v_mfma_f32_4x4x1_16b_f32 v[12:15], v72, v85, v[12:15]
	v_mfma_f32_4x4x1_16b_f32 v[16:19], v72, v93, v[16:19]
	v_and_b32_e32 v77, 0xffff0000, v77
	v_mfma_f32_4x4x1_16b_f32 v[4:7], v21, v86, v[4:7]
	v_mfma_f32_4x4x1_16b_f32 v[8:11], v21, v94, v[8:11]
	v_lshlrev_b32_e32 v30, 16, v78
	v_mfma_f32_4x4x1_16b_f32 v[12:15], v25, v86, v[12:15]
	v_mfma_f32_4x4x1_16b_f32 v[16:19], v25, v94, v[16:19]
	v_and_b32_e32 v78, 0xffff0000, v78
	v_mfma_f32_4x4x1_16b_f32 v[4:7], v69, v87, v[4:7]
	v_mfma_f32_4x4x1_16b_f32 v[8:11], v69, v95, v[8:11]
	v_lshlrev_b32_e32 v31, 16, v79
	v_mfma_f32_4x4x1_16b_f32 v[12:15], v73, v87, v[12:15]
	v_mfma_f32_4x4x1_16b_f32 v[16:19], v73, v95, v[16:19]
	v_and_b32_e32 v79, 0xffff0000, v79
	v_mfma_f32_4x4x1_16b_f32 v[4:7], v22, v88, v[4:7]
	v_mfma_f32_4x4x1_16b_f32 v[8:11], v22, v96, v[8:11]
	v_lshlrev_b32_e32 v32, 16, v80
	v_mfma_f32_4x4x1_16b_f32 v[12:15], v26, v88, v[12:15]
	v_mfma_f32_4x4x1_16b_f32 v[16:19], v26, v96, v[16:19]
	v_and_b32_e32 v80, 0xffff0000, v80
	v_mfma_f32_4x4x1_16b_f32 v[4:7], v70, v89, v[4:7]
	v_mfma_f32_4x4x1_16b_f32 v[8:11], v70, v97, v[8:11]
	v_lshlrev_b32_e32 v33, 16, v81
	v_mfma_f32_4x4x1_16b_f32 v[12:15], v74, v89, v[12:15]
	v_mfma_f32_4x4x1_16b_f32 v[16:19], v74, v97, v[16:19]
	v_and_b32_e32 v81, 0xffff0000, v81
	v_mfma_f32_4x4x1_16b_f32 v[4:7], v23, v90, v[4:7]
	v_mfma_f32_4x4x1_16b_f32 v[8:11], v23, v98, v[8:11]
	v_lshlrev_b32_e32 v34, 16, v82
	v_mfma_f32_4x4x1_16b_f32 v[12:15], v27, v90, v[12:15]
	v_mfma_f32_4x4x1_16b_f32 v[16:19], v27, v98, v[16:19]
	v_and_b32_e32 v82, 0xffff0000, v82
	v_mfma_f32_4x4x1_16b_f32 v[4:7], v71, v91, v[4:7]
	v_mfma_f32_4x4x1_16b_f32 v[8:11], v71, v99, v[8:11]
	v_lshlrev_b32_e32 v35, 16, v83
	v_mfma_f32_4x4x1_16b_f32 v[12:15], v75, v91, v[12:15]
	v_mfma_f32_4x4x1_16b_f32 v[16:19], v75, v99, v[16:19]
	v_and_b32_e32 v83, 0xffff0000, v83
	s_add_i32 s1, s13, 12
	s_and_b32 s1, s1, 15
	s_lshl_b32 s1, s1, 12
	v_add_u32_e32 v117, s1, v3
	ds_read_b128 v[84:87], v117 offset:0
	ds_read_b128 v[88:91], v117 offset:1024
	ds_read_b128 v[92:95], v117 offset:2048
	ds_read_b128 v[96:99], v117 offset:3072
	s_waitcnt vmcnt(6)
	s_waitcnt lgkmcnt(4)
	v_mfma_f32_4x4x1_16b_f32 v[4:7], v28, v100, v[4:7]
	v_mfma_f32_4x4x1_16b_f32 v[8:11], v28, v108, v[8:11]
	v_lshlrev_b32_e32 v20, 16, v36
	v_mfma_f32_4x4x1_16b_f32 v[12:15], v32, v100, v[12:15]
	v_mfma_f32_4x4x1_16b_f32 v[16:19], v32, v108, v[16:19]
	v_and_b32_e32 v36, 0xffff0000, v36
	v_mfma_f32_4x4x1_16b_f32 v[4:7], v76, v101, v[4:7]
	v_mfma_f32_4x4x1_16b_f32 v[8:11], v76, v109, v[8:11]
	v_lshlrev_b32_e32 v21, 16, v37
	v_mfma_f32_4x4x1_16b_f32 v[12:15], v80, v101, v[12:15]
	v_mfma_f32_4x4x1_16b_f32 v[16:19], v80, v109, v[16:19]
	v_and_b32_e32 v37, 0xffff0000, v37
	v_mfma_f32_4x4x1_16b_f32 v[4:7], v29, v102, v[4:7]
	v_mfma_f32_4x4x1_16b_f32 v[8:11], v29, v110, v[8:11]
	v_lshlrev_b32_e32 v22, 16, v38
	v_mfma_f32_4x4x1_16b_f32 v[12:15], v33, v102, v[12:15]
	v_mfma_f32_4x4x1_16b_f32 v[16:19], v33, v110, v[16:19]
	v_and_b32_e32 v38, 0xffff0000, v38
	v_mfma_f32_4x4x1_16b_f32 v[4:7], v77, v103, v[4:7]
	v_mfma_f32_4x4x1_16b_f32 v[8:11], v77, v111, v[8:11]
	v_lshlrev_b32_e32 v23, 16, v39
	v_mfma_f32_4x4x1_16b_f32 v[12:15], v81, v103, v[12:15]
	v_mfma_f32_4x4x1_16b_f32 v[16:19], v81, v111, v[16:19]
	v_and_b32_e32 v39, 0xffff0000, v39
	v_mfma_f32_4x4x1_16b_f32 v[4:7], v30, v104, v[4:7]
	v_mfma_f32_4x4x1_16b_f32 v[8:11], v30, v112, v[8:11]
	v_lshlrev_b32_e32 v24, 16, v40
	v_mfma_f32_4x4x1_16b_f32 v[12:15], v34, v104, v[12:15]
	v_mfma_f32_4x4x1_16b_f32 v[16:19], v34, v112, v[16:19]
	v_and_b32_e32 v40, 0xffff0000, v40
	v_mfma_f32_4x4x1_16b_f32 v[4:7], v78, v105, v[4:7]
	v_mfma_f32_4x4x1_16b_f32 v[8:11], v78, v113, v[8:11]
	v_lshlrev_b32_e32 v25, 16, v41
	v_mfma_f32_4x4x1_16b_f32 v[12:15], v82, v105, v[12:15]
	v_mfma_f32_4x4x1_16b_f32 v[16:19], v82, v113, v[16:19]
	v_and_b32_e32 v41, 0xffff0000, v41
	v_mfma_f32_4x4x1_16b_f32 v[4:7], v31, v106, v[4:7]
	v_mfma_f32_4x4x1_16b_f32 v[8:11], v31, v114, v[8:11]
	v_lshlrev_b32_e32 v26, 16, v42
	v_mfma_f32_4x4x1_16b_f32 v[12:15], v35, v106, v[12:15]
	v_mfma_f32_4x4x1_16b_f32 v[16:19], v35, v114, v[16:19]
	v_and_b32_e32 v42, 0xffff0000, v42
	v_mfma_f32_4x4x1_16b_f32 v[4:7], v79, v107, v[4:7]
	v_mfma_f32_4x4x1_16b_f32 v[8:11], v79, v115, v[8:11]
	v_lshlrev_b32_e32 v27, 16, v43
	v_mfma_f32_4x4x1_16b_f32 v[12:15], v83, v107, v[12:15]
	v_mfma_f32_4x4x1_16b_f32 v[16:19], v83, v115, v[16:19]
	v_and_b32_e32 v43, 0xffff0000, v43
	s_add_i32 s1, s13, 13
	s_and_b32 s1, s1, 15
	s_lshl_b32 s1, s1, 12
	v_add_u32_e32 v117, s1, v3
	ds_read_b128 v[100:103], v117 offset:0
	ds_read_b128 v[104:107], v117 offset:1024
	ds_read_b128 v[108:111], v117 offset:2048
	ds_read_b128 v[112:115], v117 offset:3072
	s_waitcnt vmcnt(4)
	s_waitcnt lgkmcnt(4)
; __global__ void __launch_bounds__(NWAVES * 64, 2) fwd_megakernel(Args args) {
;     ...
;                     for (int jj = 0; jj < 4; ++jj) pw[q][jj] = *(const u32x4*)(XB + (size_t)(m0 + q) * DM + 512 * jj + 8 * ln); }
; #pragma unroll
;                 for (int q = 0; q < 4; ++q) { float d = 0.f;
; #pragma unroll
;                     for (int jj = 0; jj < 4; ++jj) { const u32x4 w = pw[q][jj];
;                         d += __uint_as_float(w.x << 16) * wreg[8 * jj + 0] + __uint_as_float(w.x & 0xffff0000u) * wreg[8 * jj + 1] + __uint_as_float(w.y << 16) * wreg[8 * jj + 2] + __uint_as_float(w.y & 0xffff0000u) * wreg[8 * jj + 3]
;                            + __uint_as_float(w.z << 16) * wreg[8 * jj + 4] + __uint_as_float(w.z & 0xffff0000u) * wreg[8 * jj + 5] + __uint_as_float(w.w << 16) * wreg[8 * jj + 6] + __uint_as_float(w.w & 0xffff0000u) * wreg[8 * jj + 7]; }
	v_mfma_f32_4x4x1_16b_f32 v[4:7], v20, v84, v[4:7]
	v_mfma_f32_4x4x1_16b_f32 v[8:11], v20, v92, v[8:11]
	v_lshlrev_b32_e32 v28, 16, v44
	v_mfma_f32_4x4x1_16b_f32 v[12:15], v24, v84, v[12:15]
	v_mfma_f32_4x4x1_16b_f32 v[16:19], v24, v92, v[16:19]
	v_and_b32_e32 v44, 0xffff0000, v44
	v_mfma_f32_4x4x1_16b_f32 v[4:7], v36, v85, v[4:7]
	v_mfma_f32_4x4x1_16b_f32 v[8:11], v36, v93, v[8:11]
	v_lshlrev_b32_e32 v29, 16, v45
	v_mfma_f32_4x4x1_16b_f32 v[12:15], v40, v85, v[12:15]
	v_mfma_f32_4x4x1_16b_f32 v[16:19], v40, v93, v[16:19]
	v_and_b32_e32 v45, 0xffff0000, v45
	v_mfma_f32_4x4x1_16b_f32 v[4:7], v21, v86, v[4:7]
	v_mfma_f32_4x4x1_16b_f32 v[8:11], v21, v94, v[8:11]
	v_lshlrev_b32_e32 v30, 16, v46
	v_mfma_f32_4x4x1_16b_f32 v[12:15], v25, v86, v[12:15]
	v_mfma_f32_4x4x1_16b_f32 v[16:19], v25, v94, v[16:19]
	v_and_b32_e32 v46, 0xffff0000, v46
	v_mfma_f32_4x4x1_16b_f32 v[4:7], v37, v87, v[4:7]
	v_mfma_f32_4x4x1_16b_f32 v[8:11], v37, v95, v[8:11]
	v_lshlrev_b32_e32 v31, 16, v47
	v_mfma_f32_4x4x1_16b_f32 v[12:15], v41, v87, v[12:15]
	v_mfma_f32_4x4x1_16b_f32 v[16:19], v41, v95, v[16:19]
	v_and_b32_e32 v47, 0xffff0000, v47
	v_mfma_f32_4x4x1_16b_f32 v[4:7], v22, v88, v[4:7]
	v_mfma_f32_4x4x1_16b_f32 v[8:11], v22, v96, v[8:11]
	v_lshlrev_b32_e32 v32, 16, v48
	v_mfma_f32_4x4x1_16b_f32 v[12:15], v26, v88, v[12:15]
	v_mfma_f32_4x4x1_16b_f32 v[16:19], v26, v96, v[16:19]
	v_and_b32_e32 v48, 0xffff0000, v48
	v_mfma_f32_4x4x1_16b_f32 v[4:7], v38, v89, v[4:7]
	v_mfma_f32_4x4x1_16b_f32 v[8:11], v38, v97, v[8:11]
	v_lshlrev_b32_e32 v33, 16, v49
	v_mfma_f32_4x4x1_16b_f32 v[12:15], v42, v89, v[12:15]
	v_mfma_f32_4x4x1_16b_f32 v[16:19], v42, v97, v[16:19]
	v_and_b32_e32 v49, 0xffff0000, v49
	v_mfma_f32_4x4x1_16b_f32 v[4:7], v23, v90, v[4:7]
	v_mfma_f32_4x4x1_16b_f32 v[8:11], v23, v98, v[8:11]
	v_lshlrev_b32_e32 v34, 16, v50
	v_mfma_f32_4x4x1_16b_f32 v[12:15], v27, v90, v[12:15]
	v_mfma_f32_4x4x1_16b_f32 v[16:19], v27, v98, v[16:19]
	v_and_b32_e32 v50, 0xffff0000, v50
	v_mfma_f32_4x4x1_16b_f32 v[4:7], v39, v91, v[4:7]
	v_mfma_f32_4x4x1_16b_f32 v[8:11], v39, v99, v[8:11]
	v_lshlrev_b32_e32 v35, 16, v51
	v_mfma_f32_4x4x1_16b_f32 v[12:15], v43, v91, v[12:15]
	v_mfma_f32_4x4x1_16b_f32 v[16:19], v43, v99, v[16:19]
	v_and_b32_e32 v51, 0xffff0000, v51
	s_add_i32 s1, s13, 14
	s_and_b32 s1, s1, 15
	s_lshl_b32 s1, s1, 12
	v_add_u32_e32 v117, s1, v3
	ds_read_b128 v[84:87], v117 offset:0
	ds_read_b128 v[88:91], v117 offset:1024
	ds_read_b128 v[92:95], v117 offset:2048
	ds_read_b128 v[96:99], v117 offset:3072
	s_waitcnt vmcnt(2)
	s_waitcnt lgkmcnt(4)
	v_mfma_f32_4x4x1_16b_f32 v[4:7], v28, v100, v[4:7]
	v_mfma_f32_4x4x1_16b_f32 v[8:11], v28, v108, v[8:11]
	v_lshlrev_b32_e32 v20, 16, v52
	v_mfma_f32_4x4x1_16b_f32 v[12:15], v32, v100, v[12:15]
	v_mfma_f32_4x4x1_16b_f32 v[16:19], v32, v108, v[16:19]
	v_and_b32_e32 v52, 0xffff0000, v52
	v_mfma_f32_4x4x1_16b_f32 v[4:7], v44, v101, v[4:7]
	v_mfma_f32_4x4x1_16b_f32 v[8:11], v44, v109, v[8:11]
	v_lshlrev_b32_e32 v21, 16, v53
	v_mfma_f32_4x4x1_16b_f32 v[12:15], v48, v101, v[12:15]
	v_mfma_f32_4x4x1_16b_f32 v[16:19], v48, v109, v[16:19]
	v_and_b32_e32 v53, 0xffff0000, v53
	v_mfma_f32_4x4x1_16b_f32 v[4:7], v29, v102, v[4:7]
	v_mfma_f32_4x4x1_16b_f32 v[8:11], v29, v110, v[8:11]
	v_lshlrev_b32_e32 v22, 16, v54
	v_mfma_f32_4x4x1_16b_f32 v[12:15], v33, v102, v[12:15]
	v_mfma_f32_4x4x1_16b_f32 v[16:19], v33, v110, v[16:19]
	v_and_b32_e32 v54, 0xffff0000, v54
	v_mfma_f32_4x4x1_16b_f32 v[4:7], v45, v103, v[4:7]
	v_mfma_f32_4x4x1_16b_f32 v[8:11], v45, v111, v[8:11]
	v_lshlrev_b32_e32 v23, 16, v55
	v_mfma_f32_4x4x1_16b_f32 v[12:15], v49, v103, v[12:15]
	v_mfma_f32_4x4x1_16b_f32 v[16:19], v49, v111, v[16:19]
	v_and_b32_e32 v55, 0xffff0000, v55
	v_mfma_f32_4x4x1_16b_f32 v[4:7], v30, v104, v[4:7]
	v_mfma_f32_4x4x1_16b_f32 v[8:11], v30, v112, v[8:11]
	v_lshlrev_b32_e32 v24, 16, v56
	v_mfma_f32_4x4x1_16b_f32 v[12:15], v34, v104, v[12:15]
	v_mfma_f32_4x4x1_16b_f32 v[16:19], v34, v112, v[16:19]
	v_and_b32_e32 v56, 0xffff0000, v56
	v_mfma_f32_4x4x1_16b_f32 v[4:7], v46, v105, v[4:7]
	v_mfma_f32_4x4x1_16b_f32 v[8:11], v46, v113, v[8:11]
	v_lshlrev_b32_e32 v25, 16, v57
	v_mfma_f32_4x4x1_16b_f32 v[12:15], v50, v105, v[12:15]
	v_mfma_f32_4x4x1_16b_f32 v[16:19], v50, v113, v[16:19]
	v_and_b32_e32 v57, 0xffff0000, v57
	v_mfma_f32_4x4x1_16b_f32 v[4:7], v31, v106, v[4:7]
	v_mfma_f32_4x4x1_16b_f32 v[8:11], v31, v114, v[8:11]
	v_lshlrev_b32_e32 v26, 16, v58
	v_mfma_f32_4x4x1_16b_f32 v[12:15], v35, v106, v[12:15]
	v_mfma_f32_4x4x1_16b_f32 v[16:19], v35, v114, v[16:19]
	v_and_b32_e32 v58, 0xffff0000, v58
	v_mfma_f32_4x4x1_16b_f32 v[4:7], v47, v107, v[4:7]
	v_mfma_f32_4x4x1_16b_f32 v[8:11], v47, v115, v[8:11]
	v_lshlrev_b32_e32 v27, 16, v59
	v_mfma_f32_4x4x1_16b_f32 v[12:15], v51, v107, v[12:15]
	v_mfma_f32_4x4x1_16b_f32 v[16:19], v51, v115, v[16:19]
	v_and_b32_e32 v59, 0xffff0000, v59
	s_add_i32 s1, s13, 15
	s_and_b32 s1, s1, 15
	s_lshl_b32 s1, s1, 12
	v_add_u32_e32 v117, s1, v3
	ds_read_b128 v[100:103], v117 offset:0
	ds_read_b128 v[104:107], v117 offset:1024
	ds_read_b128 v[108:111], v117 offset:2048
	ds_read_b128 v[112:115], v117 offset:3072
	s_waitcnt vmcnt(0)
	s_waitcnt lgkmcnt(4)
; __global__ void __launch_bounds__(NWAVES * 64, 2) fwd_megakernel(Args args) {
;     ...
;                 for (int q = 0; q < 4; ++q) { float d = 0.f;
; #pragma unroll
;                     for (int jj = 0; jj < 4; ++jj) { const u32x4 w = pw[q][jj];
;                         d += __uint_as_float(w.x << 16) * wreg[8 * jj + 0] + __uint_as_float(w.x & 0xffff0000u) * wreg[8 * jj + 1] + __uint_as_float(w.y << 16) * wreg[8 * jj + 2] + __uint_as_float(w.y & 0xffff0000u) * wreg[8 * jj + 3]
;                            + __uint_as_float(w.z << 16) * wreg[8 * jj + 4] + __uint_as_float(w.z & 0xffff0000u) * wreg[8 * jj + 5] + __uint_as_float(w.w << 16) * wreg[8 * jj + 6] + __uint_as_float(w.w & 0xffff0000u) * wreg[8 * jj + 7]; }
	v_mfma_f32_4x4x1_16b_f32 v[4:7], v20, v84, v[4:7]
	v_mfma_f32_4x4x1_16b_f32 v[8:11], v20, v92, v[8:11]
	v_lshlrev_b32_e32 v28, 16, v60
	v_mfma_f32_4x4x1_16b_f32 v[12:15], v24, v84, v[12:15]
	v_mfma_f32_4x4x1_16b_f32 v[16:19], v24, v92, v[16:19]
	v_and_b32_e32 v60, 0xffff0000, v60
	v_mfma_f32_4x4x1_16b_f32 v[4:7], v52, v85, v[4:7]
	v_mfma_f32_4x4x1_16b_f32 v[8:11], v52, v93, v[8:11]
	v_lshlrev_b32_e32 v29, 16, v61
	v_mfma_f32_4x4x1_16b_f32 v[12:15], v56, v85, v[12:15]
	v_mfma_f32_4x4x1_16b_f32 v[16:19], v56, v93, v[16:19]
	v_and_b32_e32 v61, 0xffff0000, v61
	v_mfma_f32_4x4x1_16b_f32 v[4:7], v21, v86, v[4:7]
	v_mfma_f32_4x4x1_16b_f32 v[8:11], v21, v94, v[8:11]
	v_lshlrev_b32_e32 v30, 16, v62
	v_mfma_f32_4x4x1_16b_f32 v[12:15], v25, v86, v[12:15]
	v_mfma_f32_4x4x1_16b_f32 v[16:19], v25, v94, v[16:19]
	v_and_b32_e32 v62, 0xffff0000, v62
	v_mfma_f32_4x4x1_16b_f32 v[4:7], v53, v87, v[4:7]
	v_mfma_f32_4x4x1_16b_f32 v[8:11], v53, v95, v[8:11]
	v_lshlrev_b32_e32 v31, 16, v63
	v_mfma_f32_4x4x1_16b_f32 v[12:15], v57, v87, v[12:15]
	v_mfma_f32_4x4x1_16b_f32 v[16:19], v57, v95, v[16:19]
	v_and_b32_e32 v63, 0xffff0000, v63
	v_mfma_f32_4x4x1_16b_f32 v[4:7], v22, v88, v[4:7]
	v_mfma_f32_4x4x1_16b_f32 v[8:11], v22, v96, v[8:11]
	v_lshlrev_b32_e32 v32, 16, v64
	v_mfma_f32_4x4x1_16b_f32 v[12:15], v26, v88, v[12:15]
	v_mfma_f32_4x4x1_16b_f32 v[16:19], v26, v96, v[16:19]
	v_and_b32_e32 v64, 0xffff0000, v64
	v_mfma_f32_4x4x1_16b_f32 v[4:7], v54, v89, v[4:7]
	v_mfma_f32_4x4x1_16b_f32 v[8:11], v54, v97, v[8:11]
	v_lshlrev_b32_e32 v33, 16, v65
	v_mfma_f32_4x4x1_16b_f32 v[12:15], v58, v89, v[12:15]
	v_mfma_f32_4x4x1_16b_f32 v[16:19], v58, v97, v[16:19]
	v_and_b32_e32 v65, 0xffff0000, v65
	v_mfma_f32_4x4x1_16b_f32 v[4:7], v23, v90, v[4:7]
	v_mfma_f32_4x4x1_16b_f32 v[8:11], v23, v98, v[8:11]
	v_lshlrev_b32_e32 v34, 16, v66
	v_mfma_f32_4x4x1_16b_f32 v[12:15], v27, v90, v[12:15]
	v_mfma_f32_4x4x1_16b_f32 v[16:19], v27, v98, v[16:19]
	v_and_b32_e32 v66, 0xffff0000, v66
	v_mfma_f32_4x4x1_16b_f32 v[4:7], v55, v91, v[4:7]
	v_mfma_f32_4x4x1_16b_f32 v[8:11], v55, v99, v[8:11]
	v_lshlrev_b32_e32 v35, 16, v67
	v_mfma_f32_4x4x1_16b_f32 v[12:15], v59, v91, v[12:15]
	v_mfma_f32_4x4x1_16b_f32 v[16:19], v59, v99, v[16:19]
	v_and_b32_e32 v67, 0xffff0000, v67
	s_waitcnt lgkmcnt(0)
; __device__ __forceinline__ float rs_from_ss(float ss) { return rsqrtf(ss * (1.0f / DM) + RMS_EPS); }
; __global__ void __launch_bounds__(NWAVES * 64, 2) fwd_megakernel(Args args) {
;     ...
;                 for (int q = 0; q < 4; ++q) { float d = 0.f;
; #pragma unroll
;                     for (int jj = 0; jj < 4; ++jj) { const u32x4 w = pw[q][jj];
;                         d += __uint_as_float(w.x << 16) * wreg[8 * jj + 0] + __uint_as_float(w.x & 0xffff0000u) * wreg[8 * jj + 1] + __uint_as_float(w.y << 16) * wreg[8 * jj + 2] + __uint_as_float(w.y & 0xffff0000u) * wreg[8 * jj + 3]
;                            + __uint_as_float(w.z << 16) * wreg[8 * jj + 4] + __uint_as_float(w.z & 0xffff0000u) * wreg[8 * jj + 5] + __uint_as_float(w.w << 16) * wreg[8 * jj + 6] + __uint_as_float(w.w & 0xffff0000u) * wreg[8 * jj + 7]; }
;                     d = wave_sum(d);
;                     if (ln == 0) { const int m = m0 + q; const float f = d * rs_from_ss(sq[q]) + bf; const float lf = fminf(f, 0.f) - log1pf(__expf(-fabsf(f)));
;                         logfb[((size_t)(m / SEQ) * NH + wave) * SEQ + (m % SEQ)] = lf; } }
	v_mfma_f32_4x4x1_16b_f32 v[4:7], v28, v100, v[4:7]
	v_mfma_f32_4x4x1_16b_f32 v[8:11], v28, v108, v[8:11]
	v_mfma_f32_4x4x1_16b_f32 v[12:15], v32, v100, v[12:15]
	v_mfma_f32_4x4x1_16b_f32 v[16:19], v32, v108, v[16:19]
	v_mfma_f32_4x4x1_16b_f32 v[4:7], v60, v101, v[4:7]
	v_mfma_f32_4x4x1_16b_f32 v[8:11], v60, v109, v[8:11]
	v_mfma_f32_4x4x1_16b_f32 v[12:15], v64, v101, v[12:15]
	v_mfma_f32_4x4x1_16b_f32 v[16:19], v64, v109, v[16:19]
	v_mfma_f32_4x4x1_16b_f32 v[4:7], v29, v102, v[4:7]
	v_mfma_f32_4x4x1_16b_f32 v[8:11], v29, v110, v[8:11]
	v_mfma_f32_4x4x1_16b_f32 v[12:15], v33, v102, v[12:15]
	v_mfma_f32_4x4x1_16b_f32 v[16:19], v33, v110, v[16:19]
	v_mfma_f32_4x4x1_16b_f32 v[4:7], v61, v103, v[4:7]
	v_mfma_f32_4x4x1_16b_f32 v[8:11], v61, v111, v[8:11]
	v_mfma_f32_4x4x1_16b_f32 v[12:15], v65, v103, v[12:15]
	v_mfma_f32_4x4x1_16b_f32 v[16:19], v65, v111, v[16:19]
	v_mfma_f32_4x4x1_16b_f32 v[4:7], v30, v104, v[4:7]
	v_mfma_f32_4x4x1_16b_f32 v[8:11], v30, v112, v[8:11]
	v_mfma_f32_4x4x1_16b_f32 v[12:15], v34, v104, v[12:15]
	v_mfma_f32_4x4x1_16b_f32 v[16:19], v34, v112, v[16:19]
	v_mfma_f32_4x4x1_16b_f32 v[4:7], v62, v105, v[4:7]
	v_mfma_f32_4x4x1_16b_f32 v[8:11], v62, v113, v[8:11]
	v_mfma_f32_4x4x1_16b_f32 v[12:15], v66, v105, v[12:15]
	v_mfma_f32_4x4x1_16b_f32 v[16:19], v66, v113, v[16:19]
	v_mfma_f32_4x4x1_16b_f32 v[4:7], v31, v106, v[4:7]
	v_mfma_f32_4x4x1_16b_f32 v[8:11], v31, v114, v[8:11]
	v_mfma_f32_4x4x1_16b_f32 v[12:15], v35, v106, v[12:15]
	v_mfma_f32_4x4x1_16b_f32 v[16:19], v35, v114, v[16:19]
	v_mfma_f32_4x4x1_16b_f32 v[4:7], v63, v107, v[4:7]
	v_mfma_f32_4x4x1_16b_f32 v[8:11], v63, v115, v[8:11]
	v_mfma_f32_4x4x1_16b_f32 v[12:15], v67, v107, v[12:15]
	v_mfma_f32_4x4x1_16b_f32 v[16:19], v67, v115, v[16:19]
	v_lshrrev_b32_e32 v20, 3, v168
	v_and_b32_e32 v21, 7, v168
	v_lshlrev_b32_e32 v22, 2, v20
	v_lshlrev_b32_e32 v23, 2, v21
	s_lshl_b32 s5, s12, 3
	s_add_u32 s5, s5, s4
	s_lshl_b32 s1, s5, 2
	s_add_u32 s1, s1, 0x10000
	s_add_u32 s8, s60, s1
	s_addc_u32 s9, s61, 0
	global_load_dword v24, v22, s[8:9]
	global_load_dword v25, v23, s[16:17]
	s_lshl_b32 s1, s12, 12
	s_add_u32 s1, s1, 0x10000
	v_lshlrev_b32_e32 v26, 2, v168
	v_add_u32_e32 v26, s1, v26
	s_nop 7
	ds_write_b32 v26, v4 offset:0
	ds_write_b32 v26, v5 offset:256
	ds_write_b32 v26, v6 offset:512
	ds_write_b32 v26, v7 offset:768
	ds_write_b32 v26, v8 offset:1024
	ds_write_b32 v26, v9 offset:1280
	ds_write_b32 v26, v10 offset:1536
	ds_write_b32 v26, v11 offset:1792
	ds_write_b32 v26, v12 offset:2048
	ds_write_b32 v26, v13 offset:2304
	ds_write_b32 v26, v14 offset:2560
	ds_write_b32 v26, v15 offset:2816
	ds_write_b32 v26, v16 offset:3072
	ds_write_b32 v26, v17 offset:3328
	ds_write_b32 v26, v18 offset:3584
	ds_write_b32 v26, v19 offset:3840
	v_lshrrev_b32_e32 v27, 2, v20
	v_lshrrev_b32_e32 v28, 2, v21
	v_lshl_or_b32 v27, v27, 1, v28
	v_and_b32_e32 v28, 3, v20
	v_lshl_or_b32 v27, v27, 2, v28
	v_and_b32_e32 v28, 3, v21
	v_lshlrev_b32_e32 v28, 2, v28
	v_lshl_or_b32 v27, v27, 8, v28
	v_add_u32_e32 v27, s1, v27
	s_waitcnt lgkmcnt(0)
	ds_read_b32 v36, v27 offset:0
	ds_read_b32 v37, v27 offset:16
	ds_read_b32 v38, v27 offset:32
	ds_read_b32 v39, v27 offset:48
	ds_read_b32 v40, v27 offset:64
	ds_read_b32 v41, v27 offset:80
	ds_read_b32 v42, v27 offset:96
	ds_read_b32 v43, v27 offset:112
	ds_read_b32 v44, v27 offset:128
	ds_read_b32 v45, v27 offset:144
	ds_read_b32 v46, v27 offset:160
	ds_read_b32 v47, v27 offset:176
	ds_read_b32 v48, v27 offset:192
	ds_read_b32 v49, v27 offset:208
	ds_read_b32 v50, v27 offset:224
	ds_read_b32 v51, v27 offset:240
	s_lshr_b32 s1, s5, 11
	s_lshl_b32 s1, s1, 16
	s_and_b32 s5, s5, 0x7ff
	s_lshl_b32 s5, s5, 2
	s_add_u32 s1, s1, s5
	s_add_u32 s1, s1, 0x80000
	s_add_u32 s8, s60, s1
	s_addc_u32 s9, s61, 0
	v_lshl_or_b32 v29, v21, 13, v22
	s_waitcnt lgkmcnt(0)
	v_add_f32_e32 v36, v36, v44
	v_add_f32_e32 v37, v37, v45
	v_add_f32_e32 v38, v38, v46
	v_add_f32_e32 v39, v39, v47
	v_add_f32_e32 v40, v40, v48
	v_add_f32_e32 v41, v41, v49
	v_add_f32_e32 v42, v42, v50
	v_add_f32_e32 v43, v43, v51
	v_add_f32_e32 v36, v36, v40
	v_add_f32_e32 v37, v37, v41
	v_add_f32_e32 v38, v38, v42
	v_add_f32_e32 v39, v39, v43
	v_add_f32_e32 v36, v36, v38
	v_add_f32_e32 v37, v37, v39
	v_add_f32_e32 v36, v36, v37
	s_waitcnt vmcnt(0)
	v_fmamk_f32 v24, v24, 0x3a000000, v172
	v_rsq_f32_e32 v24, v24
	s_nop 0
	v_fma_f32 v30, v36, v24, v25
	v_mul_f32_e64 v31, |v30|, s18
	v_exp_f32_e32 v31, v31
	s_nop 0
	v_add_f32_e32 v32, 1.0, v31
	v_add_f32_e32 v33, -1.0, v32
	v_sub_f32_e32 v33, v33, v31
	v_log_f32_e32 v34, v32
	v_rcp_f32_e32 v35, v32
	v_mov_b32_e32 v37, 0x3eaaaaab
	v_fmac_f32_e32 v37, 0xbe800000, v31
	v_mul_f32_e32 v34, s19, v34
	v_fma_f32 v34, -v33, v35, v34
	v_fma_f32 v37, v31, v37, -0.5
	v_fma_f32 v37, v31, v37, 1.0
	v_mul_f32_e32 v37, v31, v37
	v_cmp_gt_f32_e32 vcc, 0x3c800000, v31
	v_min_f32_e32 v38, 0, v30
	s_nop 0
	v_cndmask_b32_e32 v34, v34, v37, vcc
	v_sub_f32_e32 v38, v38, v34
	global_store_dword v29, v38, s[8:9]
	s_lshl_b32 s5, s21, 4
	s_add_i32 s4, s4, s5
	s_cmpk_gt_i32 s4, 0x3fff
	s_cbranch_scc0 .Llg_trip
	s_waitcnt lgkmcnt(0)
	s_barrier
